# GEMM load segments: LDS-DMA load issued in front of the ds_read_b128 run it used to follow (22 sites); on top of v113
# baseline (speedup 1.0000x reference)
.LBB0_389:
	s_add_u32 s24, s22, 0xfffc0080
	s_addc_u32 s25, s23, -1
	s_add_i32 s35, 0, 0x10000
	s_cmp_eq_u32 s34, 12
	s_cselect_b32 s27, s21, s25
	s_cselect_b32 s26, s28, s24
	v_add_u32_e32 v128, s35, v184
	s_cselect_b32 s25, s19, s31
	s_cselect_b32 s24, s29, s30
	s_add_i32 s38, 0, 0x14000
	ds_read_b128 v[130:133], v128
	ds_read_b128 v[134:137], v128 offset:1024
	ds_read_b128 v[138:141], v128 offset:2048
	ds_read_b128 v[142:145], v128 offset:3072
	v_add_u32_e32 v128, s38, v184
	ds_read_b128 v[154:157], v128
	ds_read_b128 v[158:161], v128 offset:1024
	ds_read_b128 v[162:165], v128 offset:2048
	ds_read_b128 v[166:169], v128 offset:3072
	v_lshl_add_u64 v[206:207], s[22:23], 0, v[150:151]
	s_add_i32 m0, s73, 0xc000
	s_nop 0
	global_load_lds_dwordx4 v[206:207], off
	ds_read_b128 v[170:173], v185
	ds_read_b128 v[174:177], v185 offset:1024
	ds_read_b128 v[178:181], v185 offset:2048
	ds_read_b128 v[186:189], v185 offset:3072
	ds_read_b128 v[190:193], v185 offset:4096
	ds_read_b128 v[194:197], v185 offset:5120
	ds_read_b128 v[198:201], v185 offset:6144
	ds_read_b128 v[202:205], v185 offset:7168
	v_lshl_add_u64 v[206:207], s[22:23], 0, v[152:153]
	s_add_i32 m0, s73, 0xe000
	s_nop 0
	global_load_lds_dwordx4 v[206:207], off
	s_waitcnt vmcnt(8)
	s_waitcnt lgkmcnt(0)
	s_barrier
	s_setprio 1
	s_waitcnt lgkmcnt(0)
	v_mfma_f32_16x16x32_bf16 v[124:127], v[130:133], v[170:173], v[124:127]
	v_mfma_f32_16x16x32_bf16 v[120:123], v[138:141], v[170:173], v[120:123]
	v_mfma_f32_16x16x32_bf16 v[108:111], v[130:133], v[178:181], v[108:111]
	v_mfma_f32_16x16x32_bf16 v[104:107], v[138:141], v[178:181], v[104:107]
	v_mfma_f32_16x16x32_bf16 v[92:95], v[130:133], v[190:193], v[92:95]
	v_mfma_f32_16x16x32_bf16 v[88:91], v[138:141], v[190:193], v[88:91]
	v_mfma_f32_16x16x32_bf16 v[76:79], v[130:133], v[198:201], v[76:79]
	v_mfma_f32_16x16x32_bf16 v[72:75], v[138:141], v[198:201], v[72:75]
	v_mfma_f32_16x16x32_bf16 v[124:127], v[134:137], v[174:177], v[124:127]
	v_mfma_f32_16x16x32_bf16 v[120:123], v[142:145], v[174:177], v[120:123]
	v_mfma_f32_16x16x32_bf16 v[108:111], v[134:137], v[186:189], v[108:111]
	v_mfma_f32_16x16x32_bf16 v[104:107], v[142:145], v[186:189], v[104:107]
	v_mfma_f32_16x16x32_bf16 v[92:95], v[134:137], v[194:197], v[92:95]
	v_mfma_f32_16x16x32_bf16 v[88:91], v[142:145], v[194:197], v[88:91]
	v_mfma_f32_16x16x32_bf16 v[76:79], v[134:137], v[202:205], v[76:79]
	v_mfma_f32_16x16x32_bf16 v[72:75], v[142:145], v[202:205], v[72:75]
	s_setprio 0
	s_setprio 1
	v_mfma_f32_16x16x32_bf16 v[116:119], v[154:157], v[170:173], v[116:119]
	v_mfma_f32_16x16x32_bf16 v[112:115], v[162:165], v[170:173], v[112:115]
	v_mfma_f32_16x16x32_bf16 v[100:103], v[154:157], v[178:181], v[100:103]
	v_mfma_f32_16x16x32_bf16 v[96:99], v[162:165], v[178:181], v[96:99]
	v_mfma_f32_16x16x32_bf16 v[84:87], v[154:157], v[190:193], v[84:87]
	v_mfma_f32_16x16x32_bf16 v[80:83], v[162:165], v[190:193], v[80:83]
	v_mfma_f32_16x16x32_bf16 v[68:71], v[154:157], v[198:201], v[68:71]
	v_mfma_f32_16x16x32_bf16 v[64:67], v[162:165], v[198:201], v[64:67]
	v_mfma_f32_16x16x32_bf16 v[116:119], v[158:161], v[174:177], v[116:119]
	v_mfma_f32_16x16x32_bf16 v[112:115], v[166:169], v[174:177], v[112:115]
	v_mfma_f32_16x16x32_bf16 v[100:103], v[158:161], v[186:189], v[100:103]
	v_mfma_f32_16x16x32_bf16 v[96:99], v[166:169], v[186:189], v[96:99]
	v_mfma_f32_16x16x32_bf16 v[84:87], v[158:161], v[194:197], v[84:87]
	v_mfma_f32_16x16x32_bf16 v[80:83], v[166:169], v[194:197], v[80:83]
	v_mfma_f32_16x16x32_bf16 v[68:71], v[158:161], v[202:205], v[68:71]
	v_mfma_f32_16x16x32_bf16 v[64:67], v[166:169], v[202:205], v[64:67]
	s_setprio 0
	s_barrier
	s_add_i32 s35, s35, s4
	v_lshl_add_u64 v[206:207], s[24:25], 0, v[146:147]
	s_mov_b32 m0, s35
	s_nop 0
	global_load_lds_dwordx4 v[206:207], off
	ds_read_b128 v[170:173], v185 offset:16384
	ds_read_b128 v[174:177], v185 offset:17408
	ds_read_b128 v[178:181], v185 offset:18432
	ds_read_b128 v[186:189], v185 offset:19456
	ds_read_b128 v[190:193], v185 offset:20480
	ds_read_b128 v[194:197], v185 offset:21504
	ds_read_b128 v[198:201], v185 offset:22528
	ds_read_b128 v[202:205], v185 offset:23552
	s_add_i32 m0, s35, 0x2000
	s_add_u32 s36, s24, 0x40000
	v_lshl_add_u64 v[208:209], s[24:25], 0, v[148:149]
	s_addc_u32 s37, s25, 0
	s_add_i32 s35, s38, s4
	global_load_lds_dwordx4 v[208:209], off
	v_lshl_add_u64 v[210:211], s[36:37], 0, v[146:147]
	s_mov_b32 m0, s35
	v_lshl_add_u64 v[212:213], s[26:27], 0, v[148:149]
	global_load_lds_dwordx4 v[210:211], off
	v_lshl_add_u64 v[210:211], s[36:37], 0, v[148:149]
	s_add_i32 m0, s35, 0x2000
	s_nop 0
	global_load_lds_dwordx4 v[210:211], off
	v_lshl_add_u64 v[210:211], s[26:27], 0, v[146:147]
	s_mov_b32 m0, s73
	s_nop 0
	global_load_lds_dwordx4 v[210:211], off
	s_mov_b32 m0, s93
	s_nop 0
	global_load_lds_dwordx4 v[212:213], off
	s_waitcnt vmcnt(8)
	s_waitcnt lgkmcnt(0)
	s_barrier
	s_setprio 1
	s_waitcnt lgkmcnt(0)
	v_mfma_f32_16x16x32_bf16 v[60:63], v[130:133], v[170:173], v[60:63]
	v_mfma_f32_16x16x32_bf16 v[56:59], v[138:141], v[170:173], v[56:59]
	v_mfma_f32_16x16x32_bf16 v[44:47], v[130:133], v[178:181], v[44:47]
	v_mfma_f32_16x16x32_bf16 v[40:43], v[138:141], v[178:181], v[40:43]
	v_mfma_f32_16x16x32_bf16 v[28:31], v[130:133], v[190:193], v[28:31]
	v_mfma_f32_16x16x32_bf16 v[24:27], v[138:141], v[190:193], v[24:27]
	v_mfma_f32_16x16x32_bf16 v[12:15], v[130:133], v[198:201], v[12:15]
	v_mfma_f32_16x16x32_bf16 v[8:11], v[138:141], v[198:201], v[8:11]
	v_mfma_f32_16x16x32_bf16 v[60:63], v[134:137], v[174:177], v[60:63]
	v_mfma_f32_16x16x32_bf16 v[56:59], v[142:145], v[174:177], v[56:59]
	v_mfma_f32_16x16x32_bf16 v[44:47], v[134:137], v[186:189], v[44:47]
	v_mfma_f32_16x16x32_bf16 v[40:43], v[142:145], v[186:189], v[40:43]
	v_mfma_f32_16x16x32_bf16 v[28:31], v[134:137], v[194:197], v[28:31]
	v_mfma_f32_16x16x32_bf16 v[24:27], v[142:145], v[194:197], v[24:27]
	v_mfma_f32_16x16x32_bf16 v[12:15], v[134:137], v[202:205], v[12:15]
	v_mfma_f32_16x16x32_bf16 v[8:11], v[142:145], v[202:205], v[8:11]
	s_setprio 0
	s_setprio 1
	v_mfma_f32_16x16x32_bf16 v[52:55], v[154:157], v[170:173], v[52:55]
	v_mfma_f32_16x16x32_bf16 v[48:51], v[162:165], v[170:173], v[48:51]
	v_mfma_f32_16x16x32_bf16 v[36:39], v[154:157], v[178:181], v[36:39]
	v_mfma_f32_16x16x32_bf16 v[32:35], v[162:165], v[178:181], v[32:35]
	v_mfma_f32_16x16x32_bf16 v[20:23], v[154:157], v[190:193], v[20:23]
	v_mfma_f32_16x16x32_bf16 v[16:19], v[162:165], v[190:193], v[16:19]
	v_mfma_f32_16x16x32_bf16 v[4:7], v[154:157], v[198:201], v[4:7]
	v_mfma_f32_16x16x32_bf16 v[0:3], v[162:165], v[198:201], v[0:3]
	v_mfma_f32_16x16x32_bf16 v[52:55], v[158:161], v[174:177], v[52:55]
	v_mfma_f32_16x16x32_bf16 v[48:51], v[166:169], v[174:177], v[48:51]
	v_mfma_f32_16x16x32_bf16 v[36:39], v[158:161], v[186:189], v[36:39]
	v_mfma_f32_16x16x32_bf16 v[32:35], v[166:169], v[186:189], v[32:35]
	v_mfma_f32_16x16x32_bf16 v[20:23], v[158:161], v[194:197], v[20:23]
	v_mfma_f32_16x16x32_bf16 v[16:19], v[166:169], v[194:197], v[16:19]
	v_mfma_f32_16x16x32_bf16 v[4:7], v[158:161], v[202:205], v[4:7]
	v_mfma_f32_16x16x32_bf16 v[0:3], v[166:169], v[202:205], v[0:3]
	s_setprio 0
	s_barrier
	s_add_i32 s35, 0, 0x18000
	v_add_u32_e32 v128, s35, v184
	s_add_i32 s36, 0, 0x1c000
	ds_read_b128 v[130:133], v128
	ds_read_b128 v[134:137], v128 offset:1024
	ds_read_b128 v[138:141], v128 offset:2048
	ds_read_b128 v[142:145], v128 offset:3072
	v_add_u32_e32 v128, s36, v184
	ds_read_b128 v[154:157], v128
	ds_read_b128 v[158:161], v128 offset:1024
	ds_read_b128 v[162:165], v128 offset:2048
	ds_read_b128 v[166:169], v128 offset:3072
	s_add_u32 s26, s26, 0x40000
	s_addc_u32 s27, s27, 0
	s_mov_b32 m0, s96
	v_lshl_add_u64 v[214:215], s[26:27], 0, v[146:147]
	global_load_lds_dwordx4 v[214:215], off
	ds_read_b128 v[170:173], v185 offset:32768
	ds_read_b128 v[174:177], v185 offset:33792
	ds_read_b128 v[178:181], v185 offset:34816
	ds_read_b128 v[186:189], v185 offset:35840
	ds_read_b128 v[190:193], v185 offset:36864
	ds_read_b128 v[194:197], v185 offset:37888
	ds_read_b128 v[198:201], v185 offset:38912
	ds_read_b128 v[202:205], v185 offset:39936
	v_lshl_add_u64 v[214:215], s[26:27], 0, v[148:149]
	s_mov_b32 m0, s97
	s_nop 0
	global_load_lds_dwordx4 v[214:215], off
	s_waitcnt vmcnt(8)
	s_waitcnt lgkmcnt(0)
	s_barrier
	s_setprio 1
	s_waitcnt lgkmcnt(0)
	v_mfma_f32_16x16x32_bf16 v[124:127], v[130:133], v[170:173], v[124:127]
	v_mfma_f32_16x16x32_bf16 v[120:123], v[138:141], v[170:173], v[120:123]
	v_mfma_f32_16x16x32_bf16 v[108:111], v[130:133], v[178:181], v[108:111]
	v_mfma_f32_16x16x32_bf16 v[104:107], v[138:141], v[178:181], v[104:107]
	v_mfma_f32_16x16x32_bf16 v[92:95], v[130:133], v[190:193], v[92:95]
	v_mfma_f32_16x16x32_bf16 v[88:91], v[138:141], v[190:193], v[88:91]
	v_mfma_f32_16x16x32_bf16 v[76:79], v[130:133], v[198:201], v[76:79]
	v_mfma_f32_16x16x32_bf16 v[72:75], v[138:141], v[198:201], v[72:75]
	v_mfma_f32_16x16x32_bf16 v[124:127], v[134:137], v[174:177], v[124:127]
	v_mfma_f32_16x16x32_bf16 v[120:123], v[142:145], v[174:177], v[120:123]
	v_mfma_f32_16x16x32_bf16 v[108:111], v[134:137], v[186:189], v[108:111]
	v_mfma_f32_16x16x32_bf16 v[104:107], v[142:145], v[186:189], v[104:107]
	v_mfma_f32_16x16x32_bf16 v[92:95], v[134:137], v[194:197], v[92:95]
	v_mfma_f32_16x16x32_bf16 v[88:91], v[142:145], v[194:197], v[88:91]
	v_mfma_f32_16x16x32_bf16 v[76:79], v[134:137], v[202:205], v[76:79]
	v_mfma_f32_16x16x32_bf16 v[72:75], v[142:145], v[202:205], v[72:75]
	s_setprio 0
	s_setprio 1
	v_mfma_f32_16x16x32_bf16 v[116:119], v[154:157], v[170:173], v[116:119]
	v_mfma_f32_16x16x32_bf16 v[112:115], v[162:165], v[170:173], v[112:115]
	v_mfma_f32_16x16x32_bf16 v[100:103], v[154:157], v[178:181], v[100:103]
	v_mfma_f32_16x16x32_bf16 v[96:99], v[162:165], v[178:181], v[96:99]
	v_mfma_f32_16x16x32_bf16 v[84:87], v[154:157], v[190:193], v[84:87]
	v_mfma_f32_16x16x32_bf16 v[80:83], v[162:165], v[190:193], v[80:83]
	v_mfma_f32_16x16x32_bf16 v[68:71], v[154:157], v[198:201], v[68:71]
	v_mfma_f32_16x16x32_bf16 v[64:67], v[162:165], v[198:201], v[64:67]
	v_mfma_f32_16x16x32_bf16 v[116:119], v[158:161], v[174:177], v[116:119]
	v_mfma_f32_16x16x32_bf16 v[112:115], v[166:169], v[174:177], v[112:115]
	v_mfma_f32_16x16x32_bf16 v[100:103], v[158:161], v[186:189], v[100:103]
	v_mfma_f32_16x16x32_bf16 v[96:99], v[166:169], v[186:189], v[96:99]
	v_mfma_f32_16x16x32_bf16 v[84:87], v[158:161], v[194:197], v[84:87]
	v_mfma_f32_16x16x32_bf16 v[80:83], v[166:169], v[194:197], v[80:83]
	v_mfma_f32_16x16x32_bf16 v[68:71], v[158:161], v[202:205], v[68:71]
	v_mfma_f32_16x16x32_bf16 v[64:67], v[166:169], v[202:205], v[64:67]
	s_setprio 0
	s_barrier
	s_add_i32 s26, s35, s4
	v_lshl_add_u64 v[206:207], v[206:207], 0, s[6:7]
	s_mov_b32 m0, s26
	s_nop 0
	global_load_lds_dwordx4 v[206:207], off
	ds_read_b128 v[170:173], v185 offset:49152
	ds_read_b128 v[174:177], v185 offset:50176
	ds_read_b128 v[178:181], v185 offset:51200
	ds_read_b128 v[186:189], v185 offset:52224
	ds_read_b128 v[190:193], v185 offset:53248
	ds_read_b128 v[194:197], v185 offset:54272
	ds_read_b128 v[198:201], v185 offset:55296
	ds_read_b128 v[202:205], v185 offset:56320
	s_add_i32 m0, s26, 0x2000
	s_add_u32 s24, s24, 0x40080
	v_lshl_add_u64 v[206:207], v[208:209], 0, s[6:7]
	s_addc_u32 s25, s25, 0
	s_add_i32 s26, s36, s4
	global_load_lds_dwordx4 v[206:207], off
	v_lshl_add_u64 v[206:207], s[24:25], 0, v[146:147]
	s_mov_b32 m0, s26
	s_nop 0
	global_load_lds_dwordx4 v[206:207], off
	v_lshl_add_u64 v[206:207], s[24:25], 0, v[148:149]
	s_add_i32 m0, s26, 0x2000
	s_nop 0
	global_load_lds_dwordx4 v[206:207], off
	v_lshl_add_u64 v[206:207], v[210:211], 0, s[6:7]
	s_mov_b32 m0, s85
	s_nop 0
	global_load_lds_dwordx4 v[206:207], off
	v_lshl_add_u64 v[206:207], v[212:213], 0, s[6:7]
	s_mov_b32 m0, s62
	s_nop 0
	global_load_lds_dwordx4 v[206:207], off
	s_waitcnt vmcnt(8)
	s_waitcnt lgkmcnt(0)
	s_barrier
	s_setprio 1
	s_waitcnt lgkmcnt(0)
	v_mfma_f32_16x16x32_bf16 v[60:63], v[130:133], v[170:173], v[60:63]
	v_mfma_f32_16x16x32_bf16 v[56:59], v[138:141], v[170:173], v[56:59]
	v_mfma_f32_16x16x32_bf16 v[44:47], v[130:133], v[178:181], v[44:47]
	v_mfma_f32_16x16x32_bf16 v[40:43], v[138:141], v[178:181], v[40:43]
	v_mfma_f32_16x16x32_bf16 v[28:31], v[130:133], v[190:193], v[28:31]
	v_mfma_f32_16x16x32_bf16 v[24:27], v[138:141], v[190:193], v[24:27]
	v_mfma_f32_16x16x32_bf16 v[12:15], v[130:133], v[198:201], v[12:15]
	v_mfma_f32_16x16x32_bf16 v[8:11], v[138:141], v[198:201], v[8:11]
	v_mfma_f32_16x16x32_bf16 v[60:63], v[134:137], v[174:177], v[60:63]
	v_mfma_f32_16x16x32_bf16 v[56:59], v[142:145], v[174:177], v[56:59]
	v_mfma_f32_16x16x32_bf16 v[44:47], v[134:137], v[186:189], v[44:47]
	v_mfma_f32_16x16x32_bf16 v[40:43], v[142:145], v[186:189], v[40:43]
	v_mfma_f32_16x16x32_bf16 v[28:31], v[134:137], v[194:197], v[28:31]
	v_mfma_f32_16x16x32_bf16 v[24:27], v[142:145], v[194:197], v[24:27]
	v_mfma_f32_16x16x32_bf16 v[12:15], v[134:137], v[202:205], v[12:15]
	v_mfma_f32_16x16x32_bf16 v[8:11], v[142:145], v[202:205], v[8:11]
	s_setprio 0
	s_setprio 1
	v_mfma_f32_16x16x32_bf16 v[52:55], v[154:157], v[170:173], v[52:55]
	v_mfma_f32_16x16x32_bf16 v[48:51], v[162:165], v[170:173], v[48:51]
	v_mfma_f32_16x16x32_bf16 v[36:39], v[154:157], v[178:181], v[36:39]
	v_mfma_f32_16x16x32_bf16 v[32:35], v[162:165], v[178:181], v[32:35]
	v_mfma_f32_16x16x32_bf16 v[20:23], v[154:157], v[190:193], v[20:23]
	v_mfma_f32_16x16x32_bf16 v[16:19], v[162:165], v[190:193], v[16:19]
	v_mfma_f32_16x16x32_bf16 v[4:7], v[154:157], v[198:201], v[4:7]
	v_mfma_f32_16x16x32_bf16 v[0:3], v[162:165], v[198:201], v[0:3]
	v_mfma_f32_16x16x32_bf16 v[52:55], v[158:161], v[174:177], v[52:55]
	v_mfma_f32_16x16x32_bf16 v[48:51], v[166:169], v[174:177], v[48:51]
	v_mfma_f32_16x16x32_bf16 v[36:39], v[158:161], v[186:189], v[36:39]
	v_mfma_f32_16x16x32_bf16 v[32:35], v[166:169], v[186:189], v[32:35]
	v_mfma_f32_16x16x32_bf16 v[20:23], v[158:161], v[194:197], v[20:23]
	v_mfma_f32_16x16x32_bf16 v[16:19], v[166:169], v[194:197], v[16:19]
	v_mfma_f32_16x16x32_bf16 v[4:7], v[158:161], v[202:205], v[4:7]
	v_mfma_f32_16x16x32_bf16 v[0:3], v[166:169], v[202:205], v[0:3]
	s_setprio 0
	s_barrier
	s_add_i32 s34, s34, 2
	s_add_u32 s22, s22, 0x100
	s_addc_u32 s23, s23, 0
	s_add_u32 s30, s30, 0x100
	s_addc_u32 s31, s31, 0
	s_cmp_gt_u32 s34, 13
	s_cbranch_scc0 .LBB0_389
	s_and_b64 vcc, exec, s[58:59]
	s_cbranch_vccz .LBB0_392
	s_barrier

.LBB0_935:
	v_add_u32_e32 v142, 0x10000, v249
	v_add_u32_e32 v146, 0x14000, v249
	ds_read_b128 v[130:133], v142
	ds_read_b128 v[134:137], v142 offset:1024
	ds_read_b128 v[138:141], v142 offset:2048
	ds_read_b128 v[142:145], v142 offset:3072
	ds_read_b128 v[150:153], v146
	ds_read_b128 v[154:157], v146 offset:1024
	ds_read_b128 v[158:161], v146 offset:2048
	ds_read_b128 v[146:149], v146 offset:3072
	s_waitcnt lgkmcnt(0)
	v_lshl_add_u64 v[194:195], v[240:241], 0, s[18:19]
	s_add_i32 m0, s26, 0xc000
	s_nop 0
	global_load_lds_dwordx4 v[194:195], off
	ds_read_b128 v[186:189], v246
	ds_read_b128 v[190:193], v246 offset:1024
	ds_read_b128 v[178:181], v246 offset:2048
	ds_read_b128 v[182:185], v246 offset:3072
	ds_read_b128 v[170:173], v246 offset:4096
	ds_read_b128 v[174:177], v246 offset:5120
	ds_read_b128 v[162:165], v246 offset:6144
	ds_read_b128 v[166:169], v246 offset:7168
	v_lshl_add_u64 v[194:195], v[242:243], 0, s[18:19]
	s_add_i32 m0, s26, 0xe000
	s_nop 0
	global_load_lds_dwordx4 v[194:195], off
	s_waitcnt vmcnt(8)
	s_waitcnt lgkmcnt(0)
	s_barrier
	s_setprio 1
	s_setprio 0
	s_mov_b64 s[20:21], -1
	s_and_b64 vcc, exec, s[56:57]
	s_cbranch_vccz .LBB0_937
	s_waitcnt lgkmcnt(0)
	v_mfma_f32_16x16x32_bf16 v[194:197], v[150:153], v[186:189], v[116:119]
	s_mov_b64 s[20:21], 0
	v_mfma_f32_16x16x32_bf16 v[198:201], v[158:161], v[186:189], v[112:115]
	v_mfma_f32_16x16x32_bf16 v[202:205], v[150:153], v[178:181], v[108:111]
	v_mfma_f32_16x16x32_bf16 v[206:209], v[158:161], v[178:181], v[104:107]
	v_mfma_f32_16x16x32_bf16 v[210:213], v[150:153], v[170:173], v[100:103]
	v_mfma_f32_16x16x32_bf16 v[214:217], v[158:161], v[170:173], v[96:99]
	v_mfma_f32_16x16x32_bf16 v[218:221], v[150:153], v[162:165], v[72:75]
	v_mfma_f32_16x16x32_bf16 v[222:225], v[158:161], v[162:165], v[64:67]
	v_mfma_f32_16x16x32_bf16 v[194:197], v[154:157], v[190:193], v[194:197]
	v_mfma_f32_16x16x32_bf16 v[198:201], v[146:149], v[190:193], v[198:201]
	v_mfma_f32_16x16x32_bf16 v[202:205], v[154:157], v[182:185], v[202:205]
	v_mfma_f32_16x16x32_bf16 v[206:209], v[146:149], v[182:185], v[206:209]
	v_mfma_f32_16x16x32_bf16 v[210:213], v[154:157], v[174:177], v[210:213]
	v_mfma_f32_16x16x32_bf16 v[214:217], v[146:149], v[174:177], v[214:217]
	v_mfma_f32_16x16x32_bf16 v[218:221], v[154:157], v[166:169], v[218:221]
	v_mfma_f32_16x16x32_bf16 v[222:225], v[146:149], v[166:169], v[222:225]

.LBB0_940:
	s_add_u32 s20, s44, s18
	s_addc_u32 s21, s45, s19
	s_add_u32 s20, s20, 0x4800100
	s_addc_u32 s21, s21, 0
	s_add_u32 s24, s46, s18
	s_addc_u32 s25, s47, s19
	s_cmpk_eq_i32 s18, 0x700
	s_cselect_b32 s23, s17, s21
	s_cselect_b32 s22, s16, s20
	s_cselect_b32 s21, s15, s25
	s_cselect_b32 s20, s14, s24
	s_barrier
	s_mov_b32 m0, s27
	v_lshl_add_u64 v[226:227], s[20:21], 0, v[128:129]
	s_add_u32 s24, s20, 0x40000
	s_waitcnt lgkmcnt(0)
	global_load_lds_dwordx4 v[226:227], off
	ds_read_b128 v[186:189], v246 offset:16384
	ds_read_b128 v[190:193], v246 offset:17408
	ds_read_b128 v[178:181], v246 offset:18432
	ds_read_b128 v[182:185], v246 offset:19456
	ds_read_b128 v[170:173], v246 offset:20480
	ds_read_b128 v[174:177], v246 offset:21504
	ds_read_b128 v[162:165], v246 offset:22528
	ds_read_b128 v[166:169], v246 offset:23552
	v_lshl_add_u64 v[228:229], s[20:21], 0, v[238:239]
	s_mov_b32 m0, s28
	s_addc_u32 s25, s21, 0
	global_load_lds_dwordx4 v[228:229], off
	v_lshl_add_u64 v[194:195], s[24:25], 0, v[128:129]
	s_mov_b32 m0, s29
	v_lshl_add_u64 v[230:231], s[22:23], 0, v[128:129]
	global_load_lds_dwordx4 v[194:195], off
	v_lshl_add_u64 v[194:195], s[24:25], 0, v[238:239]
	s_mov_b32 m0, s30
	v_lshl_add_u64 v[232:233], s[22:23], 0, v[238:239]
	global_load_lds_dwordx4 v[194:195], off
	s_mov_b32 m0, s26
	s_nop 0
	global_load_lds_dwordx4 v[230:231], off
	s_mov_b32 m0, s31
	s_nop 0
	global_load_lds_dwordx4 v[232:233], off
	s_waitcnt vmcnt(8)
	s_waitcnt lgkmcnt(0)
	s_barrier
	s_setprio 1
	s_setprio 0
	s_mov_b64 s[24:25], -1
	s_and_b64 vcc, exec, s[56:57]
	s_cbranch_vccz .LBB0_942
	s_waitcnt lgkmcnt(0)
	v_mfma_f32_16x16x32_bf16 v[194:197], v[150:153], v[186:189], v[76:79]
	s_mov_b64 s[24:25], 0
	v_mfma_f32_16x16x32_bf16 v[202:205], v[150:153], v[178:181], v[44:47]
	v_mfma_f32_16x16x32_bf16 v[210:213], v[150:153], v[170:173], v[36:39]
	v_mfma_f32_16x16x32_bf16 v[150:153], v[150:153], v[162:165], v[12:15]
	v_mfma_f32_16x16x32_bf16 v[198:201], v[158:161], v[186:189], v[68:71]
	v_mfma_f32_16x16x32_bf16 v[206:209], v[158:161], v[178:181], v[40:43]
	v_mfma_f32_16x16x32_bf16 v[214:217], v[158:161], v[170:173], v[32:35]
	v_mfma_f32_16x16x32_bf16 v[218:221], v[154:157], v[166:169], v[150:153]
	v_mfma_f32_16x16x32_bf16 v[150:153], v[158:161], v[162:165], v[8:11]
	v_mfma_f32_16x16x32_bf16 v[194:197], v[154:157], v[190:193], v[194:197]
	v_mfma_f32_16x16x32_bf16 v[198:201], v[146:149], v[190:193], v[198:201]
	v_mfma_f32_16x16x32_bf16 v[202:205], v[154:157], v[182:185], v[202:205]
	v_mfma_f32_16x16x32_bf16 v[206:209], v[146:149], v[182:185], v[206:209]
	v_mfma_f32_16x16x32_bf16 v[210:213], v[154:157], v[174:177], v[210:213]
	v_mfma_f32_16x16x32_bf16 v[214:217], v[146:149], v[174:177], v[214:217]
	v_mfma_f32_16x16x32_bf16 v[222:225], v[146:149], v[166:169], v[150:153]

.LBB0_945:
	s_barrier
	v_add_u32_e32 v130, 0x18000, v249
	ds_read_b128 v[138:141], v130
	ds_read_b128 v[142:145], v130 offset:1024
	ds_read_b128 v[146:149], v130 offset:2048
	ds_read_b128 v[150:153], v130 offset:3072
	v_add_u32_e32 v130, 0x1c000, v249
	ds_read_b128 v[158:161], v130
	s_waitcnt lgkmcnt(0)
	ds_read_b128 v[162:165], v130 offset:1024
	ds_read_b128 v[166:169], v130 offset:2048
	ds_read_b128 v[154:157], v130 offset:3072
	s_add_u32 s22, s22, 0x40000
	s_addc_u32 s23, s23, 0
	s_mov_b32 m0, s34
	v_lshl_add_u64 v[130:131], s[22:23], 0, v[128:129]
	global_load_lds_dwordx4 v[130:131], off
	ds_read_b128 v[194:197], v246 offset:32768
	ds_read_b128 v[198:201], v246 offset:33792
	ds_read_b128 v[186:189], v246 offset:34816
	ds_read_b128 v[190:193], v246 offset:35840
	ds_read_b128 v[178:181], v246 offset:36864
	ds_read_b128 v[182:185], v246 offset:37888
	ds_read_b128 v[174:177], v246 offset:38912
	ds_read_b128 v[170:173], v246 offset:39936
	v_lshl_add_u64 v[130:131], s[22:23], 0, v[238:239]
	s_mov_b32 m0, s35
	s_nop 0
	global_load_lds_dwordx4 v[130:131], off
	s_waitcnt vmcnt(8)
	s_waitcnt lgkmcnt(0)
	s_barrier
	s_setprio 1
	s_setprio 0
	s_mov_b64 s[22:23], -1
	s_and_b64 vcc, exec, s[56:57]
	s_cbranch_vccz .LBB0_947
	s_waitcnt lgkmcnt(0)
	v_mfma_f32_16x16x32_bf16 v[130:133], v[158:161], v[194:197], v[116:119]
	s_mov_b64 s[22:23], 0
	v_mfma_f32_16x16x32_bf16 v[134:137], v[162:165], v[198:201], v[130:133]
	v_mfma_f32_16x16x32_bf16 v[130:133], v[166:169], v[194:197], v[112:115]
	v_mfma_f32_16x16x32_bf16 v[202:205], v[158:161], v[186:189], v[108:111]
	v_mfma_f32_16x16x32_bf16 v[206:209], v[166:169], v[186:189], v[104:107]
	v_mfma_f32_16x16x32_bf16 v[210:213], v[158:161], v[178:181], v[100:103]
	v_mfma_f32_16x16x32_bf16 v[214:217], v[166:169], v[178:181], v[96:99]
	v_mfma_f32_16x16x32_bf16 v[218:221], v[158:161], v[174:177], v[72:75]
	v_mfma_f32_16x16x32_bf16 v[222:225], v[166:169], v[174:177], v[64:67]
	v_mfma_f32_16x16x32_bf16 v[130:133], v[154:157], v[198:201], v[130:133]
	v_mfma_f32_16x16x32_bf16 v[202:205], v[162:165], v[190:193], v[202:205]
	v_mfma_f32_16x16x32_bf16 v[206:209], v[154:157], v[190:193], v[206:209]
	v_mfma_f32_16x16x32_bf16 v[210:213], v[162:165], v[182:185], v[210:213]
	v_mfma_f32_16x16x32_bf16 v[214:217], v[154:157], v[182:185], v[214:217]
	v_mfma_f32_16x16x32_bf16 v[218:221], v[162:165], v[170:173], v[218:221]
	v_mfma_f32_16x16x32_bf16 v[222:225], v[154:157], v[170:173], v[222:225]

.LBB0_950:
	s_barrier
	s_mov_b32 m0, s37
	v_lshl_add_u64 v[202:203], v[226:227], 0, s[6:7]
	s_add_u32 s20, s20, 0x40080
	s_waitcnt lgkmcnt(0)
	global_load_lds_dwordx4 v[202:203], off
	ds_read_b128 v[194:197], v246 offset:49152
	ds_read_b128 v[198:201], v246 offset:50176
	ds_read_b128 v[186:189], v246 offset:51200
	ds_read_b128 v[190:193], v246 offset:52224
	ds_read_b128 v[178:181], v246 offset:53248
	ds_read_b128 v[182:185], v246 offset:54272
	ds_read_b128 v[170:173], v246 offset:55296
	ds_read_b128 v[174:177], v246 offset:56320
	v_lshl_add_u64 v[202:203], v[228:229], 0, s[6:7]
	s_mov_b32 m0, s38
	s_addc_u32 s21, s21, 0
	global_load_lds_dwordx4 v[202:203], off
	v_lshl_add_u64 v[202:203], s[20:21], 0, v[128:129]
	s_mov_b32 m0, s5
	s_nop 0
	global_load_lds_dwordx4 v[202:203], off
	v_lshl_add_u64 v[202:203], s[20:21], 0, v[238:239]
	s_mov_b32 m0, s41
	s_nop 0
	global_load_lds_dwordx4 v[202:203], off
	v_lshl_add_u64 v[202:203], v[230:231], 0, s[6:7]
	s_mov_b32 m0, s39
	s_nop 0
	global_load_lds_dwordx4 v[202:203], off
	v_lshl_add_u64 v[202:203], v[232:233], 0, s[6:7]
	s_mov_b32 m0, s40
	s_nop 0
	global_load_lds_dwordx4 v[202:203], off
	s_waitcnt vmcnt(8)
	s_waitcnt lgkmcnt(0)
	s_barrier
	s_setprio 1
	s_setprio 0
	s_mov_b64 s[20:21], -1
	s_and_b64 vcc, exec, s[56:57]
	s_cbranch_vccz .LBB0_952
	s_waitcnt lgkmcnt(0)
	v_mfma_f32_16x16x32_bf16 v[202:205], v[158:161], v[194:197], v[76:79]
	s_mov_b64 s[20:21], 0
	v_mfma_f32_16x16x32_bf16 v[210:213], v[158:161], v[186:189], v[44:47]
	v_mfma_f32_16x16x32_bf16 v[218:221], v[158:161], v[178:181], v[36:39]
	v_mfma_f32_16x16x32_bf16 v[158:161], v[158:161], v[170:173], v[12:15]
	v_mfma_f32_16x16x32_bf16 v[206:209], v[166:169], v[194:197], v[68:71]
	v_mfma_f32_16x16x32_bf16 v[214:217], v[166:169], v[186:189], v[40:43]
	v_mfma_f32_16x16x32_bf16 v[222:225], v[166:169], v[178:181], v[32:35]
	v_mfma_f32_16x16x32_bf16 v[226:229], v[162:165], v[174:177], v[158:161]
	v_mfma_f32_16x16x32_bf16 v[158:161], v[166:169], v[170:173], v[8:11]
	v_mfma_f32_16x16x32_bf16 v[202:205], v[162:165], v[198:201], v[202:205]
	v_mfma_f32_16x16x32_bf16 v[206:209], v[154:157], v[198:201], v[206:209]
	v_mfma_f32_16x16x32_bf16 v[210:213], v[162:165], v[190:193], v[210:213]
	v_mfma_f32_16x16x32_bf16 v[214:217], v[154:157], v[190:193], v[214:217]
	v_mfma_f32_16x16x32_bf16 v[218:221], v[162:165], v[182:185], v[218:221]
	v_mfma_f32_16x16x32_bf16 v[222:225], v[154:157], v[182:185], v[222:225]
	v_mfma_f32_16x16x32_bf16 v[230:233], v[154:157], v[174:177], v[158:161]

.Lpc1_skb_1:
	v_lshl_add_u64 v[206:207], s[30:31], 0, v[202:203]
	s_add_i32 m0, s39, 0xc000
	s_nop 0
	global_load_lds_dwordx4 v[206:207], off
	ds_read_b128 v[186:189], v217
	ds_read_b128 v[190:193], v217 offset:1024
	ds_read_b128 v[178:181], v217 offset:2048
	ds_read_b128 v[182:185], v217 offset:3072
	ds_read_b128 v[170:173], v217 offset:4096
	ds_read_b128 v[174:177], v217 offset:5120
	ds_read_b128 v[162:165], v217 offset:6144
	ds_read_b128 v[166:169], v217 offset:7168
	v_lshl_add_u64 v[206:207], s[30:31], 0, v[204:205]
	s_add_i32 m0, s39, 0xe000
	v_cndmask_b32_e64 v128, 0, 1, s[52:53]
	global_load_lds_dwordx4 v[206:207], off
	s_waitcnt vmcnt(6)
	s_waitcnt lgkmcnt(0)
	v_cmp_ne_u32_e64 s[44:45], 1, v128
	s_andn2_b64 vcc, exec, s[52:53]
	s_barrier
	s_cbranch_vccnz .LBB0_1283
	s_setprio 1
	s_waitcnt lgkmcnt(0)
	v_mfma_f32_16x16x32_bf16 v[124:127], v[146:149], v[186:189], v[124:127]
	v_mfma_f32_16x16x32_bf16 v[120:123], v[154:157], v[186:189], v[120:123]
	v_mfma_f32_16x16x32_bf16 v[108:111], v[146:149], v[178:181], v[108:111]
	v_mfma_f32_16x16x32_bf16 v[104:107], v[154:157], v[178:181], v[104:107]
	v_mfma_f32_16x16x32_bf16 v[92:95], v[146:149], v[170:173], v[92:95]
	v_mfma_f32_16x16x32_bf16 v[88:91], v[154:157], v[170:173], v[88:91]
	v_mfma_f32_16x16x32_bf16 v[76:79], v[146:149], v[162:165], v[76:79]
	v_mfma_f32_16x16x32_bf16 v[72:75], v[154:157], v[162:165], v[72:75]
	v_mfma_f32_16x16x32_bf16 v[124:127], v[150:153], v[190:193], v[124:127]
	v_mfma_f32_16x16x32_bf16 v[120:123], v[158:161], v[190:193], v[120:123]
	v_mfma_f32_16x16x32_bf16 v[108:111], v[150:153], v[182:185], v[108:111]
	v_mfma_f32_16x16x32_bf16 v[104:107], v[158:161], v[182:185], v[104:107]
	v_mfma_f32_16x16x32_bf16 v[92:95], v[150:153], v[174:177], v[92:95]
	v_mfma_f32_16x16x32_bf16 v[88:91], v[158:161], v[174:177], v[88:91]
	v_mfma_f32_16x16x32_bf16 v[76:79], v[150:153], v[166:169], v[76:79]
	v_mfma_f32_16x16x32_bf16 v[72:75], v[158:161], v[166:169], v[72:75]
	s_setprio 0

.Lpc1_skb_3:
	s_add_u32 s36, s36, 0x20000
	s_addc_u32 s37, s37, 0
	s_mov_b32 m0, s61
	v_lshl_add_u64 v[218:219], s[36:37], 0, v[200:201]
	global_load_lds_dwordx4 v[218:219], off
	ds_read_b128 v[186:189], v217 offset:32768
	ds_read_b128 v[190:193], v217 offset:33792
	ds_read_b128 v[178:181], v217 offset:34816
	ds_read_b128 v[182:185], v217 offset:35840
	ds_read_b128 v[170:173], v217 offset:36864
	ds_read_b128 v[174:177], v217 offset:37888
	ds_read_b128 v[162:165], v217 offset:38912
	ds_read_b128 v[166:169], v217 offset:39936
	v_lshl_add_u64 v[218:219], s[36:37], 0, v[196:197]
	s_mov_b32 m0, s62
	s_and_b64 vcc, exec, s[44:45]
	global_load_lds_dwordx4 v[218:219], off
	s_waitcnt vmcnt(6)
	s_waitcnt lgkmcnt(0)
	s_barrier
	s_cbranch_vccnz .LBB0_1291
	s_setprio 1
	s_waitcnt lgkmcnt(0)
	v_mfma_f32_16x16x32_bf16 v[124:127], v[146:149], v[186:189], v[124:127]
	v_mfma_f32_16x16x32_bf16 v[120:123], v[154:157], v[186:189], v[120:123]
	v_mfma_f32_16x16x32_bf16 v[108:111], v[146:149], v[178:181], v[108:111]
	v_mfma_f32_16x16x32_bf16 v[104:107], v[154:157], v[178:181], v[104:107]
	v_mfma_f32_16x16x32_bf16 v[92:95], v[146:149], v[170:173], v[92:95]
	v_mfma_f32_16x16x32_bf16 v[88:91], v[154:157], v[170:173], v[88:91]
	v_mfma_f32_16x16x32_bf16 v[76:79], v[146:149], v[162:165], v[76:79]
	v_mfma_f32_16x16x32_bf16 v[72:75], v[154:157], v[162:165], v[72:75]
	v_mfma_f32_16x16x32_bf16 v[124:127], v[150:153], v[190:193], v[124:127]
	v_mfma_f32_16x16x32_bf16 v[120:123], v[158:161], v[190:193], v[120:123]
	v_mfma_f32_16x16x32_bf16 v[108:111], v[150:153], v[182:185], v[108:111]
	v_mfma_f32_16x16x32_bf16 v[104:107], v[158:161], v[182:185], v[104:107]
	v_mfma_f32_16x16x32_bf16 v[92:95], v[150:153], v[174:177], v[92:95]
	v_mfma_f32_16x16x32_bf16 v[88:91], v[158:161], v[174:177], v[88:91]
	v_mfma_f32_16x16x32_bf16 v[76:79], v[150:153], v[166:169], v[76:79]
	v_mfma_f32_16x16x32_bf16 v[72:75], v[158:161], v[166:169], v[72:75]
	s_setprio 0

.LBB0_1501:
	s_add_i32 s75, s36, 2
	s_add_u32 s34, s30, 0x100
	s_addc_u32 s35, s31, 0
	s_add_i32 s76, 0, 0x10000
	s_cmp_eq_u32 s1, s36
	s_cselect_b32 s41, s25, s35
	s_cselect_b32 s40, s71, s34
	s_cselect_b32 s37, s23, s74
	s_cselect_b32 s36, s72, s73
	s_add_i32 s77, 0, 0x14000
	v_add_u32_e32 v152, s76, v138
	v_add_u32_e32 v168, s77, v138
	ds_read_b128 v[140:143], v152
	ds_read_b128 v[144:147], v152 offset:1024
	ds_read_b128 v[148:151], v152 offset:2048
	ds_read_b128 v[152:155], v152 offset:3072
	ds_read_b128 v[156:159], v168
	ds_read_b128 v[160:163], v168 offset:1024
	ds_read_b128 v[164:167], v168 offset:2048
	ds_read_b128 v[168:171], v168 offset:3072
	v_lshl_add_u64 v[204:205], s[30:31], 0, v[132:133]
	s_add_i32 m0, s58, 0xc000
	s_nop 0
	global_load_lds_dwordx4 v[204:205], off
	ds_read_b128 v[172:175], v139
	ds_read_b128 v[176:179], v139 offset:1024
	ds_read_b128 v[180:183], v139 offset:2048
	ds_read_b128 v[184:187], v139 offset:3072
	ds_read_b128 v[188:191], v139 offset:4096
	ds_read_b128 v[192:195], v139 offset:5120
	ds_read_b128 v[196:199], v139 offset:6144
	ds_read_b128 v[200:203], v139 offset:7168
	v_lshl_add_u64 v[204:205], s[30:31], 0, v[134:135]
	s_add_i32 m0, s58, 0xe000
	s_nop 0
	global_load_lds_dwordx4 v[204:205], off
	s_waitcnt vmcnt(8)
	s_waitcnt lgkmcnt(0)
	s_barrier
	s_setprio 1
	s_waitcnt lgkmcnt(0)
	v_mfma_f32_16x16x32_bf16 v[124:127], v[140:143], v[172:175], v[124:127]
	v_mfma_f32_16x16x32_bf16 v[108:111], v[148:151], v[172:175], v[108:111]
	v_mfma_f32_16x16x32_bf16 v[120:123], v[140:143], v[180:183], v[120:123]
	v_mfma_f32_16x16x32_bf16 v[104:107], v[148:151], v[180:183], v[104:107]
	v_mfma_f32_16x16x32_bf16 v[116:119], v[140:143], v[188:191], v[116:119]
	v_mfma_f32_16x16x32_bf16 v[100:103], v[148:151], v[188:191], v[100:103]
	v_mfma_f32_16x16x32_bf16 v[112:115], v[140:143], v[196:199], v[112:115]
	v_mfma_f32_16x16x32_bf16 v[96:99], v[148:151], v[196:199], v[96:99]
	v_mfma_f32_16x16x32_bf16 v[124:127], v[144:147], v[176:179], v[124:127]
	v_mfma_f32_16x16x32_bf16 v[108:111], v[152:155], v[176:179], v[108:111]
	v_mfma_f32_16x16x32_bf16 v[120:123], v[144:147], v[184:187], v[120:123]
	v_mfma_f32_16x16x32_bf16 v[104:107], v[152:155], v[184:187], v[104:107]
	v_mfma_f32_16x16x32_bf16 v[116:119], v[144:147], v[192:195], v[116:119]
	v_mfma_f32_16x16x32_bf16 v[100:103], v[152:155], v[192:195], v[100:103]
	v_mfma_f32_16x16x32_bf16 v[112:115], v[144:147], v[200:203], v[112:115]
	v_mfma_f32_16x16x32_bf16 v[96:99], v[152:155], v[200:203], v[96:99]
	s_setprio 0
	s_setprio 1
	v_mfma_f32_16x16x32_bf16 v[92:95], v[156:159], v[172:175], v[92:95]
	v_mfma_f32_16x16x32_bf16 v[76:79], v[164:167], v[172:175], v[76:79]
	v_mfma_f32_16x16x32_bf16 v[88:91], v[156:159], v[180:183], v[88:91]
	v_mfma_f32_16x16x32_bf16 v[72:75], v[164:167], v[180:183], v[72:75]
	v_mfma_f32_16x16x32_bf16 v[84:87], v[156:159], v[188:191], v[84:87]
	v_mfma_f32_16x16x32_bf16 v[68:71], v[164:167], v[188:191], v[68:71]
	v_mfma_f32_16x16x32_bf16 v[80:83], v[156:159], v[196:199], v[80:83]
	v_mfma_f32_16x16x32_bf16 v[64:67], v[164:167], v[196:199], v[64:67]
	v_mfma_f32_16x16x32_bf16 v[92:95], v[160:163], v[176:179], v[92:95]
	v_mfma_f32_16x16x32_bf16 v[76:79], v[168:171], v[176:179], v[76:79]
	v_mfma_f32_16x16x32_bf16 v[88:91], v[160:163], v[184:187], v[88:91]
	v_mfma_f32_16x16x32_bf16 v[72:75], v[168:171], v[184:187], v[72:75]
	v_mfma_f32_16x16x32_bf16 v[84:87], v[160:163], v[192:195], v[84:87]
	v_mfma_f32_16x16x32_bf16 v[68:71], v[168:171], v[192:195], v[68:71]
	v_mfma_f32_16x16x32_bf16 v[80:83], v[160:163], v[200:203], v[80:83]
	v_mfma_f32_16x16x32_bf16 v[64:67], v[168:171], v[200:203], v[64:67]
	s_setprio 0
	s_barrier
	s_add_i32 s30, s76, s56
	v_lshl_add_u64 v[204:205], s[36:37], 0, v[128:129]
	s_mov_b32 m0, s30
	s_nop 0
	global_load_lds_dwordx4 v[204:205], off
	ds_read_b128 v[172:175], v139 offset:16384
	ds_read_b128 v[176:179], v139 offset:17408
	ds_read_b128 v[180:183], v139 offset:18432
	ds_read_b128 v[184:187], v139 offset:19456
	ds_read_b128 v[188:191], v139 offset:20480
	ds_read_b128 v[192:195], v139 offset:21504
	ds_read_b128 v[196:199], v139 offset:22528
	ds_read_b128 v[200:203], v139 offset:23552
	s_add_i32 m0, s30, 0x2000
	s_add_u32 s30, s36, 0x40000
	v_lshl_add_u64 v[206:207], s[36:37], 0, v[130:131]
	s_addc_u32 s31, s37, 0
	s_add_i32 s76, s77, s56
	global_load_lds_dwordx4 v[206:207], off
	v_lshl_add_u64 v[208:209], s[30:31], 0, v[128:129]
	s_mov_b32 m0, s76
	v_lshl_add_u64 v[210:211], s[40:41], 0, v[130:131]
	global_load_lds_dwordx4 v[208:209], off
	v_lshl_add_u64 v[208:209], s[30:31], 0, v[130:131]
	s_add_i32 m0, s76, 0x2000
	s_nop 0
	global_load_lds_dwordx4 v[208:209], off
	v_lshl_add_u64 v[208:209], s[40:41], 0, v[128:129]
	s_mov_b32 m0, s58
	s_nop 0
	global_load_lds_dwordx4 v[208:209], off
	s_mov_b32 m0, s60
	s_nop 0
	global_load_lds_dwordx4 v[210:211], off
	s_waitcnt vmcnt(8)
	s_waitcnt lgkmcnt(0)
	s_barrier
	s_setprio 1
	s_waitcnt lgkmcnt(0)
	v_mfma_f32_16x16x32_bf16 v[60:63], v[140:143], v[172:175], v[60:63]
	v_mfma_f32_16x16x32_bf16 v[44:47], v[148:151], v[172:175], v[44:47]
	v_mfma_f32_16x16x32_bf16 v[56:59], v[140:143], v[180:183], v[56:59]
	v_mfma_f32_16x16x32_bf16 v[40:43], v[148:151], v[180:183], v[40:43]
	v_mfma_f32_16x16x32_bf16 v[52:55], v[140:143], v[188:191], v[52:55]
	v_mfma_f32_16x16x32_bf16 v[36:39], v[148:151], v[188:191], v[36:39]
	v_mfma_f32_16x16x32_bf16 v[48:51], v[140:143], v[196:199], v[48:51]
	v_mfma_f32_16x16x32_bf16 v[32:35], v[148:151], v[196:199], v[32:35]
	v_mfma_f32_16x16x32_bf16 v[60:63], v[144:147], v[176:179], v[60:63]
	v_mfma_f32_16x16x32_bf16 v[44:47], v[152:155], v[176:179], v[44:47]
	v_mfma_f32_16x16x32_bf16 v[56:59], v[144:147], v[184:187], v[56:59]
	v_mfma_f32_16x16x32_bf16 v[40:43], v[152:155], v[184:187], v[40:43]
	v_mfma_f32_16x16x32_bf16 v[52:55], v[144:147], v[192:195], v[52:55]
	v_mfma_f32_16x16x32_bf16 v[36:39], v[152:155], v[192:195], v[36:39]
	v_mfma_f32_16x16x32_bf16 v[48:51], v[144:147], v[200:203], v[48:51]
	v_mfma_f32_16x16x32_bf16 v[32:35], v[152:155], v[200:203], v[32:35]
	s_setprio 0
	s_setprio 1
	v_mfma_f32_16x16x32_bf16 v[28:31], v[156:159], v[172:175], v[28:31]
	v_mfma_f32_16x16x32_bf16 v[12:15], v[164:167], v[172:175], v[12:15]
	v_mfma_f32_16x16x32_bf16 v[24:27], v[156:159], v[180:183], v[24:27]
	v_mfma_f32_16x16x32_bf16 v[8:11], v[164:167], v[180:183], v[8:11]
	v_mfma_f32_16x16x32_bf16 v[20:23], v[156:159], v[188:191], v[20:23]
	v_mfma_f32_16x16x32_bf16 v[4:7], v[164:167], v[188:191], v[4:7]
	v_mfma_f32_16x16x32_bf16 v[16:19], v[156:159], v[196:199], v[16:19]
	v_mfma_f32_16x16x32_bf16 v[0:3], v[164:167], v[196:199], v[0:3]
	v_mfma_f32_16x16x32_bf16 v[28:31], v[160:163], v[176:179], v[28:31]
	v_mfma_f32_16x16x32_bf16 v[12:15], v[168:171], v[176:179], v[12:15]
	v_mfma_f32_16x16x32_bf16 v[24:27], v[160:163], v[184:187], v[24:27]
	v_mfma_f32_16x16x32_bf16 v[8:11], v[168:171], v[184:187], v[8:11]
	v_mfma_f32_16x16x32_bf16 v[20:23], v[160:163], v[192:195], v[20:23]
	v_mfma_f32_16x16x32_bf16 v[4:7], v[168:171], v[192:195], v[4:7]
	v_mfma_f32_16x16x32_bf16 v[16:19], v[160:163], v[200:203], v[16:19]
	v_mfma_f32_16x16x32_bf16 v[0:3], v[168:171], v[200:203], v[0:3]
	s_setprio 0
	s_barrier
	s_add_i32 s76, 0, 0x18000
	s_add_i32 s77, 0, 0x1c000
	v_add_u32_e32 v152, s76, v138
	v_add_u32_e32 v168, s77, v138
	ds_read_b128 v[140:143], v152
	ds_read_b128 v[144:147], v152 offset:1024
	ds_read_b128 v[148:151], v152 offset:2048
	ds_read_b128 v[152:155], v152 offset:3072
	ds_read_b128 v[156:159], v168
	ds_read_b128 v[160:163], v168 offset:1024
	ds_read_b128 v[164:167], v168 offset:2048
	ds_read_b128 v[168:171], v168 offset:3072
	s_add_u32 s30, s40, 0x40000
	s_addc_u32 s31, s41, 0
	s_mov_b32 m0, s61
	v_lshl_add_u64 v[212:213], s[30:31], 0, v[128:129]
	global_load_lds_dwordx4 v[212:213], off
	ds_read_b128 v[172:175], v139 offset:32768
	ds_read_b128 v[176:179], v139 offset:33792
	ds_read_b128 v[180:183], v139 offset:34816
	ds_read_b128 v[184:187], v139 offset:35840
	ds_read_b128 v[188:191], v139 offset:36864
	ds_read_b128 v[192:195], v139 offset:37888
	ds_read_b128 v[196:199], v139 offset:38912
	ds_read_b128 v[200:203], v139 offset:39936
	v_lshl_add_u64 v[212:213], s[30:31], 0, v[130:131]
	s_mov_b32 m0, s62
	s_nop 0
	global_load_lds_dwordx4 v[212:213], off
	s_waitcnt vmcnt(8)
	s_waitcnt lgkmcnt(0)
	s_barrier
	s_setprio 1
	s_waitcnt lgkmcnt(0)
	v_mfma_f32_16x16x32_bf16 v[124:127], v[140:143], v[172:175], v[124:127]
	v_mfma_f32_16x16x32_bf16 v[108:111], v[148:151], v[172:175], v[108:111]
	v_mfma_f32_16x16x32_bf16 v[120:123], v[140:143], v[180:183], v[120:123]
	v_mfma_f32_16x16x32_bf16 v[104:107], v[148:151], v[180:183], v[104:107]
	v_mfma_f32_16x16x32_bf16 v[116:119], v[140:143], v[188:191], v[116:119]
	v_mfma_f32_16x16x32_bf16 v[100:103], v[148:151], v[188:191], v[100:103]
	v_mfma_f32_16x16x32_bf16 v[112:115], v[140:143], v[196:199], v[112:115]
	v_mfma_f32_16x16x32_bf16 v[96:99], v[148:151], v[196:199], v[96:99]
	v_mfma_f32_16x16x32_bf16 v[124:127], v[144:147], v[176:179], v[124:127]
	v_mfma_f32_16x16x32_bf16 v[108:111], v[152:155], v[176:179], v[108:111]
	v_mfma_f32_16x16x32_bf16 v[120:123], v[144:147], v[184:187], v[120:123]
	v_mfma_f32_16x16x32_bf16 v[104:107], v[152:155], v[184:187], v[104:107]
	v_mfma_f32_16x16x32_bf16 v[116:119], v[144:147], v[192:195], v[116:119]
	v_mfma_f32_16x16x32_bf16 v[100:103], v[152:155], v[192:195], v[100:103]
	v_mfma_f32_16x16x32_bf16 v[112:115], v[144:147], v[200:203], v[112:115]
	v_mfma_f32_16x16x32_bf16 v[96:99], v[152:155], v[200:203], v[96:99]
	s_setprio 0
	s_setprio 1
	v_mfma_f32_16x16x32_bf16 v[92:95], v[156:159], v[172:175], v[92:95]
	v_mfma_f32_16x16x32_bf16 v[76:79], v[164:167], v[172:175], v[76:79]
	v_mfma_f32_16x16x32_bf16 v[88:91], v[156:159], v[180:183], v[88:91]
	v_mfma_f32_16x16x32_bf16 v[72:75], v[164:167], v[180:183], v[72:75]
	v_mfma_f32_16x16x32_bf16 v[84:87], v[156:159], v[188:191], v[84:87]
	v_mfma_f32_16x16x32_bf16 v[68:71], v[164:167], v[188:191], v[68:71]
	v_mfma_f32_16x16x32_bf16 v[80:83], v[156:159], v[196:199], v[80:83]
	v_mfma_f32_16x16x32_bf16 v[64:67], v[164:167], v[196:199], v[64:67]
	v_mfma_f32_16x16x32_bf16 v[92:95], v[160:163], v[176:179], v[92:95]
	v_mfma_f32_16x16x32_bf16 v[76:79], v[168:171], v[176:179], v[76:79]
	v_mfma_f32_16x16x32_bf16 v[88:91], v[160:163], v[184:187], v[88:91]
	v_mfma_f32_16x16x32_bf16 v[72:75], v[168:171], v[184:187], v[72:75]
	v_mfma_f32_16x16x32_bf16 v[84:87], v[160:163], v[192:195], v[84:87]
	v_mfma_f32_16x16x32_bf16 v[68:71], v[168:171], v[192:195], v[68:71]
	v_mfma_f32_16x16x32_bf16 v[80:83], v[160:163], v[200:203], v[80:83]
	v_mfma_f32_16x16x32_bf16 v[64:67], v[168:171], v[200:203], v[64:67]
	s_setprio 0
	s_barrier
	s_add_i32 s30, s76, s56
	v_lshl_add_u64 v[204:205], v[204:205], 0, s[6:7]
	s_mov_b32 m0, s30
	s_nop 0
	global_load_lds_dwordx4 v[204:205], off
	ds_read_b128 v[172:175], v139 offset:49152
	ds_read_b128 v[176:179], v139 offset:50176
	ds_read_b128 v[180:183], v139 offset:51200
	ds_read_b128 v[184:187], v139 offset:52224
	ds_read_b128 v[188:191], v139 offset:53248
	ds_read_b128 v[192:195], v139 offset:54272
	ds_read_b128 v[196:199], v139 offset:55296
	ds_read_b128 v[200:203], v139 offset:56320
	s_add_i32 m0, s30, 0x2000
	s_add_u32 s30, s36, 0x40080
	v_lshl_add_u64 v[204:205], v[206:207], 0, s[6:7]
	s_addc_u32 s31, s37, 0
	s_add_i32 s36, s77, s56
	global_load_lds_dwordx4 v[204:205], off
	v_lshl_add_u64 v[204:205], s[30:31], 0, v[128:129]
	s_mov_b32 m0, s36
	s_nop 0
	global_load_lds_dwordx4 v[204:205], off
	v_lshl_add_u64 v[204:205], s[30:31], 0, v[130:131]
	s_add_i32 m0, s36, 0x2000
	s_nop 0
	global_load_lds_dwordx4 v[204:205], off
	v_lshl_add_u64 v[204:205], v[208:209], 0, s[6:7]
	s_mov_b32 m0, s63
	s_nop 0
	global_load_lds_dwordx4 v[204:205], off
	v_lshl_add_u64 v[204:205], v[210:211], 0, s[6:7]
	s_mov_b32 m0, s64
	s_nop 0
	global_load_lds_dwordx4 v[204:205], off
	s_waitcnt vmcnt(8)
	s_waitcnt lgkmcnt(0)
	s_barrier
	s_setprio 1
	s_waitcnt lgkmcnt(0)
	v_mfma_f32_16x16x32_bf16 v[60:63], v[140:143], v[172:175], v[60:63]
	v_mfma_f32_16x16x32_bf16 v[44:47], v[148:151], v[172:175], v[44:47]
	v_mfma_f32_16x16x32_bf16 v[56:59], v[140:143], v[180:183], v[56:59]
	v_mfma_f32_16x16x32_bf16 v[40:43], v[148:151], v[180:183], v[40:43]
	v_mfma_f32_16x16x32_bf16 v[52:55], v[140:143], v[188:191], v[52:55]
	v_mfma_f32_16x16x32_bf16 v[36:39], v[148:151], v[188:191], v[36:39]
	v_mfma_f32_16x16x32_bf16 v[48:51], v[140:143], v[196:199], v[48:51]
	v_mfma_f32_16x16x32_bf16 v[32:35], v[148:151], v[196:199], v[32:35]
	v_mfma_f32_16x16x32_bf16 v[60:63], v[144:147], v[176:179], v[60:63]
	v_mfma_f32_16x16x32_bf16 v[44:47], v[152:155], v[176:179], v[44:47]
	v_mfma_f32_16x16x32_bf16 v[56:59], v[144:147], v[184:187], v[56:59]
	v_mfma_f32_16x16x32_bf16 v[40:43], v[152:155], v[184:187], v[40:43]
	v_mfma_f32_16x16x32_bf16 v[52:55], v[144:147], v[192:195], v[52:55]
	v_mfma_f32_16x16x32_bf16 v[36:39], v[152:155], v[192:195], v[36:39]
	v_mfma_f32_16x16x32_bf16 v[48:51], v[144:147], v[200:203], v[48:51]
	v_mfma_f32_16x16x32_bf16 v[32:35], v[152:155], v[200:203], v[32:35]
	s_setprio 0
	s_setprio 1
	v_mfma_f32_16x16x32_bf16 v[28:31], v[156:159], v[172:175], v[28:31]
	v_mfma_f32_16x16x32_bf16 v[12:15], v[164:167], v[172:175], v[12:15]
	v_mfma_f32_16x16x32_bf16 v[24:27], v[156:159], v[180:183], v[24:27]
	v_mfma_f32_16x16x32_bf16 v[8:11], v[164:167], v[180:183], v[8:11]
	v_mfma_f32_16x16x32_bf16 v[20:23], v[156:159], v[188:191], v[20:23]
	v_mfma_f32_16x16x32_bf16 v[4:7], v[164:167], v[188:191], v[4:7]
	v_mfma_f32_16x16x32_bf16 v[16:19], v[156:159], v[196:199], v[16:19]
	v_mfma_f32_16x16x32_bf16 v[0:3], v[164:167], v[196:199], v[0:3]
	v_mfma_f32_16x16x32_bf16 v[28:31], v[160:163], v[176:179], v[28:31]
	v_mfma_f32_16x16x32_bf16 v[12:15], v[168:171], v[176:179], v[12:15]
	v_mfma_f32_16x16x32_bf16 v[24:27], v[160:163], v[184:187], v[24:27]
	v_mfma_f32_16x16x32_bf16 v[8:11], v[168:171], v[184:187], v[8:11]
	v_mfma_f32_16x16x32_bf16 v[20:23], v[160:163], v[192:195], v[20:23]
	v_mfma_f32_16x16x32_bf16 v[4:7], v[168:171], v[192:195], v[4:7]
	v_mfma_f32_16x16x32_bf16 v[16:19], v[160:163], v[200:203], v[16:19]
	v_mfma_f32_16x16x32_bf16 v[0:3], v[168:171], v[200:203], v[0:3]
	s_setprio 0
	s_barrier
	s_add_u32 s73, s73, 0x100
	s_addc_u32 s74, s74, 0
	s_cmp_ge_u32 s75, s92
	s_mov_b64 s[30:31], s[34:35]
	s_mov_b32 s36, s75
	s_cbranch_scc0 .LBB0_1501
	s_andn2_b64 vcc, exec, s[50:51]
	s_cbranch_vccnz .LBB0_1493
	v_mov_b32_e32 v0, 0
	s_mov_b32 s66, s22
	s_mov_b32 s65, s24
	s_mov_b64 s[18:19], s[28:29]
	s_mov_b64 s[20:21], s[26:27]
	s_mov_b32 s68, s70
	v_mov_b32_e32 v1, v0
	v_mov_b32_e32 v2, v0
	v_mov_b32_e32 v3, v0
	v_mov_b32_e32 v16, v0
	v_mov_b32_e32 v17, v0
	v_mov_b32_e32 v18, v0
	v_mov_b32_e32 v19, v0
	v_mov_b32_e32 v4, v0
	v_mov_b32_e32 v5, v0
	v_mov_b32_e32 v6, v0
	v_mov_b32_e32 v7, v0
	v_mov_b32_e32 v20, v0
	v_mov_b32_e32 v21, v0
	v_mov_b32_e32 v22, v0
	v_mov_b32_e32 v23, v0
	v_mov_b32_e32 v8, v0
	v_mov_b32_e32 v9, v0
	v_mov_b32_e32 v10, v0
	v_mov_b32_e32 v11, v0
	v_mov_b32_e32 v24, v0
	v_mov_b32_e32 v25, v0
	v_mov_b32_e32 v26, v0
	v_mov_b32_e32 v27, v0
	v_mov_b32_e32 v12, v0
	v_mov_b32_e32 v13, v0
	v_mov_b32_e32 v14, v0
	v_mov_b32_e32 v15, v0
	v_mov_b32_e32 v28, v0
	v_mov_b32_e32 v29, v0
	v_mov_b32_e32 v30, v0
	v_mov_b32_e32 v31, v0
	v_mov_b32_e32 v32, v0
	v_mov_b32_e32 v33, v0
	v_mov_b32_e32 v34, v0
	v_mov_b32_e32 v35, v0
	v_mov_b32_e32 v48, v0
	v_mov_b32_e32 v49, v0
	v_mov_b32_e32 v50, v0
	v_mov_b32_e32 v51, v0
	v_mov_b32_e32 v36, v0
	v_mov_b32_e32 v37, v0
	v_mov_b32_e32 v38, v0
	v_mov_b32_e32 v39, v0
	v_mov_b32_e32 v52, v0
	v_mov_b32_e32 v53, v0
	v_mov_b32_e32 v54, v0
	v_mov_b32_e32 v55, v0
	v_mov_b32_e32 v40, v0
	v_mov_b32_e32 v41, v0
	v_mov_b32_e32 v42, v0
	v_mov_b32_e32 v43, v0
	v_mov_b32_e32 v56, v0
	v_mov_b32_e32 v57, v0
	v_mov_b32_e32 v58, v0
	v_mov_b32_e32 v59, v0
	v_mov_b32_e32 v44, v0
	v_mov_b32_e32 v45, v0
	v_mov_b32_e32 v46, v0
	v_mov_b32_e32 v47, v0
	v_mov_b32_e32 v60, v0
	v_mov_b32_e32 v61, v0
	v_mov_b32_e32 v62, v0
	v_mov_b32_e32 v63, v0
	v_mov_b32_e32 v64, v0
	v_mov_b32_e32 v65, v0
	v_mov_b32_e32 v66, v0
	v_mov_b32_e32 v67, v0
	v_mov_b32_e32 v80, v0
	v_mov_b32_e32 v81, v0
	v_mov_b32_e32 v82, v0
	v_mov_b32_e32 v83, v0
	v_mov_b32_e32 v68, v0
	v_mov_b32_e32 v69, v0
	v_mov_b32_e32 v70, v0
	v_mov_b32_e32 v71, v0
	v_mov_b32_e32 v84, v0
	v_mov_b32_e32 v85, v0
	v_mov_b32_e32 v86, v0
	v_mov_b32_e32 v87, v0
	v_mov_b32_e32 v72, v0
	v_mov_b32_e32 v73, v0
	v_mov_b32_e32 v74, v0
	v_mov_b32_e32 v75, v0
	v_mov_b32_e32 v88, v0
	v_mov_b32_e32 v89, v0
	v_mov_b32_e32 v90, v0
	v_mov_b32_e32 v91, v0
	v_mov_b32_e32 v76, v0
	v_mov_b32_e32 v77, v0
	v_mov_b32_e32 v78, v0
	v_mov_b32_e32 v79, v0
	v_mov_b32_e32 v92, v0
	v_mov_b32_e32 v93, v0
	v_mov_b32_e32 v94, v0
	v_mov_b32_e32 v95, v0
	v_mov_b32_e32 v96, v0
	v_mov_b32_e32 v97, v0
	v_mov_b32_e32 v98, v0
	v_mov_b32_e32 v99, v0
	v_mov_b32_e32 v112, v0
	v_mov_b32_e32 v113, v0
	v_mov_b32_e32 v114, v0
	v_mov_b32_e32 v115, v0
	v_mov_b32_e32 v100, v0
	v_mov_b32_e32 v101, v0
	v_mov_b32_e32 v102, v0
	v_mov_b32_e32 v103, v0
	v_mov_b32_e32 v116, v0
	v_mov_b32_e32 v117, v0
	v_mov_b32_e32 v118, v0
	v_mov_b32_e32 v119, v0
	v_mov_b32_e32 v104, v0
	v_mov_b32_e32 v105, v0
	v_mov_b32_e32 v106, v0
	v_mov_b32_e32 v107, v0
	v_mov_b32_e32 v120, v0
	v_mov_b32_e32 v121, v0
	v_mov_b32_e32 v122, v0
	v_mov_b32_e32 v123, v0
	v_mov_b32_e32 v108, v0
	v_mov_b32_e32 v109, v0
	v_mov_b32_e32 v110, v0
	v_mov_b32_e32 v111, v0
	v_mov_b32_e32 v124, v0
	v_mov_b32_e32 v125, v0
	v_mov_b32_e32 v126, v0
	v_mov_b32_e32 v127, v0
	s_branch .LBB0_1493

.LBB0_1766:
	s_add_u32 s34, s30, 0xfffc0080
	s_addc_u32 s35, s31, -1
	s_add_i32 s70, 0, 0x10000
	s_cmp_eq_u32 s66, 12
	s_cselect_b32 s37, s25, s35
	s_cselect_b32 s36, s62, s34
	v_add_u32_e32 v140, s70, v144
	s_cselect_b32 s35, s23, s65
	s_cselect_b32 s34, s63, s64
	s_add_i32 s72, 0, 0x14000
	ds_read_b128 v[146:149], v140
	ds_read_b128 v[150:153], v140 offset:1024
	ds_read_b128 v[154:157], v140 offset:2048
	ds_read_b128 v[158:161], v140 offset:3072
	v_add_u32_e32 v140, s72, v144
	ds_read_b128 v[162:165], v140
	ds_read_b128 v[166:169], v140 offset:1024
	ds_read_b128 v[170:173], v140 offset:2048
	ds_read_b128 v[174:177], v140 offset:3072
	v_lshl_add_u64 v[140:141], s[30:31], 0, v[136:137]
	s_add_i32 m0, s50, 0xc000
	s_nop 0
	global_load_lds_dwordx4 v[140:141], off
	ds_read_b128 v[178:181], v145
	ds_read_b128 v[182:185], v145 offset:1024
	ds_read_b128 v[186:189], v145 offset:2048
	ds_read_b128 v[190:193], v145 offset:3072
	ds_read_b128 v[194:197], v145 offset:4096
	ds_read_b128 v[198:201], v145 offset:5120
	ds_read_b128 v[202:205], v145 offset:6144
	ds_read_b128 v[206:209], v145 offset:7168
	v_lshl_add_u64 v[140:141], s[30:31], 0, v[138:139]
	s_add_i32 m0, s50, 0xe000
	s_nop 0
	global_load_lds_dwordx4 v[140:141], off
	s_waitcnt vmcnt(8)
	s_waitcnt lgkmcnt(0)
	s_barrier
	s_setprio 1
	s_waitcnt lgkmcnt(0)
	v_mfma_f32_16x16x32_bf16 v[124:127], v[146:149], v[178:181], v[124:127]
	v_mfma_f32_16x16x32_bf16 v[120:123], v[154:157], v[178:181], v[120:123]
	v_mfma_f32_16x16x32_bf16 v[108:111], v[146:149], v[186:189], v[108:111]
	v_mfma_f32_16x16x32_bf16 v[104:107], v[154:157], v[186:189], v[104:107]
	v_mfma_f32_16x16x32_bf16 v[92:95], v[146:149], v[194:197], v[92:95]
	v_mfma_f32_16x16x32_bf16 v[88:91], v[154:157], v[194:197], v[88:91]
	v_mfma_f32_16x16x32_bf16 v[76:79], v[146:149], v[202:205], v[76:79]
	v_mfma_f32_16x16x32_bf16 v[72:75], v[154:157], v[202:205], v[72:75]
	v_mfma_f32_16x16x32_bf16 v[124:127], v[150:153], v[182:185], v[124:127]
	v_mfma_f32_16x16x32_bf16 v[120:123], v[158:161], v[182:185], v[120:123]
	v_mfma_f32_16x16x32_bf16 v[108:111], v[150:153], v[190:193], v[108:111]
	v_mfma_f32_16x16x32_bf16 v[104:107], v[158:161], v[190:193], v[104:107]
	v_mfma_f32_16x16x32_bf16 v[92:95], v[150:153], v[198:201], v[92:95]
	v_mfma_f32_16x16x32_bf16 v[88:91], v[158:161], v[198:201], v[88:91]
	v_mfma_f32_16x16x32_bf16 v[76:79], v[150:153], v[206:209], v[76:79]
	v_mfma_f32_16x16x32_bf16 v[72:75], v[158:161], v[206:209], v[72:75]
	s_setprio 0
	s_setprio 1
	v_mfma_f32_16x16x32_bf16 v[116:119], v[162:165], v[178:181], v[116:119]
	v_mfma_f32_16x16x32_bf16 v[112:115], v[170:173], v[178:181], v[112:115]
	v_mfma_f32_16x16x32_bf16 v[100:103], v[162:165], v[186:189], v[100:103]
	v_mfma_f32_16x16x32_bf16 v[96:99], v[170:173], v[186:189], v[96:99]
	v_mfma_f32_16x16x32_bf16 v[84:87], v[162:165], v[194:197], v[84:87]
	v_mfma_f32_16x16x32_bf16 v[80:83], v[170:173], v[194:197], v[80:83]
	v_mfma_f32_16x16x32_bf16 v[68:71], v[162:165], v[202:205], v[68:71]
	v_mfma_f32_16x16x32_bf16 v[64:67], v[170:173], v[202:205], v[64:67]
	v_mfma_f32_16x16x32_bf16 v[116:119], v[166:169], v[182:185], v[116:119]
	v_mfma_f32_16x16x32_bf16 v[112:115], v[174:177], v[182:185], v[112:115]
	v_mfma_f32_16x16x32_bf16 v[100:103], v[166:169], v[190:193], v[100:103]
	v_mfma_f32_16x16x32_bf16 v[96:99], v[174:177], v[190:193], v[96:99]
	v_mfma_f32_16x16x32_bf16 v[84:87], v[166:169], v[198:201], v[84:87]
	v_mfma_f32_16x16x32_bf16 v[80:83], v[174:177], v[198:201], v[80:83]
	v_mfma_f32_16x16x32_bf16 v[68:71], v[166:169], v[206:209], v[68:71]
	v_mfma_f32_16x16x32_bf16 v[64:67], v[174:177], v[206:209], v[64:67]
	s_setprio 0
	s_barrier
	s_add_i32 s70, s70, s41
	v_lshl_add_u64 v[140:141], s[34:35], 0, v[128:129]
	s_mov_b32 m0, s70
	s_nop 0
	global_load_lds_dwordx4 v[140:141], off
	ds_read_b128 v[178:181], v145 offset:16384
	ds_read_b128 v[182:185], v145 offset:17408
	ds_read_b128 v[186:189], v145 offset:18432
	ds_read_b128 v[190:193], v145 offset:19456
	ds_read_b128 v[194:197], v145 offset:20480
	ds_read_b128 v[198:201], v145 offset:21504
	ds_read_b128 v[202:205], v145 offset:22528
	ds_read_b128 v[206:209], v145 offset:23552
	s_add_i32 m0, s70, 0x2000
	s_add_u32 s70, s34, 0x40000
	v_lshl_add_u64 v[210:211], s[34:35], 0, v[130:131]
	s_addc_u32 s71, s35, 0
	s_add_i32 s72, s72, s41
	global_load_lds_dwordx4 v[210:211], off
	v_lshl_add_u64 v[212:213], s[70:71], 0, v[128:129]
	s_mov_b32 m0, s72
	v_lshl_add_u64 v[214:215], s[36:37], 0, v[132:133]
	global_load_lds_dwordx4 v[212:213], off
	v_lshl_add_u64 v[212:213], s[70:71], 0, v[130:131]
	s_add_i32 m0, s72, 0x2000
	s_nop 0
	global_load_lds_dwordx4 v[212:213], off
	v_lshl_add_u64 v[212:213], s[36:37], 0, v[134:135]
	s_mov_b32 m0, s50
	s_nop 0
	global_load_lds_dwordx4 v[212:213], off
	s_mov_b32 m0, s51
	s_nop 0
	global_load_lds_dwordx4 v[214:215], off
	s_waitcnt vmcnt(8)
	s_waitcnt lgkmcnt(0)
	s_barrier
	s_setprio 1
	s_waitcnt lgkmcnt(0)
	v_mfma_f32_16x16x32_bf16 v[60:63], v[146:149], v[178:181], v[60:63]
	v_mfma_f32_16x16x32_bf16 v[56:59], v[154:157], v[178:181], v[56:59]
	v_mfma_f32_16x16x32_bf16 v[44:47], v[146:149], v[186:189], v[44:47]
	v_mfma_f32_16x16x32_bf16 v[40:43], v[154:157], v[186:189], v[40:43]
	v_mfma_f32_16x16x32_bf16 v[28:31], v[146:149], v[194:197], v[28:31]
	v_mfma_f32_16x16x32_bf16 v[24:27], v[154:157], v[194:197], v[24:27]
	v_mfma_f32_16x16x32_bf16 v[12:15], v[146:149], v[202:205], v[12:15]
	v_mfma_f32_16x16x32_bf16 v[8:11], v[154:157], v[202:205], v[8:11]
	v_mfma_f32_16x16x32_bf16 v[60:63], v[150:153], v[182:185], v[60:63]
	v_mfma_f32_16x16x32_bf16 v[56:59], v[158:161], v[182:185], v[56:59]
	v_mfma_f32_16x16x32_bf16 v[44:47], v[150:153], v[190:193], v[44:47]
	v_mfma_f32_16x16x32_bf16 v[40:43], v[158:161], v[190:193], v[40:43]
	v_mfma_f32_16x16x32_bf16 v[28:31], v[150:153], v[198:201], v[28:31]
	v_mfma_f32_16x16x32_bf16 v[24:27], v[158:161], v[198:201], v[24:27]
	v_mfma_f32_16x16x32_bf16 v[12:15], v[150:153], v[206:209], v[12:15]
	v_mfma_f32_16x16x32_bf16 v[8:11], v[158:161], v[206:209], v[8:11]
	s_setprio 0
	s_setprio 1
	v_mfma_f32_16x16x32_bf16 v[52:55], v[162:165], v[178:181], v[52:55]
	v_mfma_f32_16x16x32_bf16 v[48:51], v[170:173], v[178:181], v[48:51]
	v_mfma_f32_16x16x32_bf16 v[36:39], v[162:165], v[186:189], v[36:39]
	v_mfma_f32_16x16x32_bf16 v[32:35], v[170:173], v[186:189], v[32:35]
	v_mfma_f32_16x16x32_bf16 v[20:23], v[162:165], v[194:197], v[20:23]
	v_mfma_f32_16x16x32_bf16 v[16:19], v[170:173], v[194:197], v[16:19]
	v_mfma_f32_16x16x32_bf16 v[4:7], v[162:165], v[202:205], v[4:7]
	v_mfma_f32_16x16x32_bf16 v[0:3], v[170:173], v[202:205], v[0:3]
	v_mfma_f32_16x16x32_bf16 v[52:55], v[166:169], v[182:185], v[52:55]
	v_mfma_f32_16x16x32_bf16 v[48:51], v[174:177], v[182:185], v[48:51]
	v_mfma_f32_16x16x32_bf16 v[36:39], v[166:169], v[190:193], v[36:39]
	v_mfma_f32_16x16x32_bf16 v[32:35], v[174:177], v[190:193], v[32:35]
	v_mfma_f32_16x16x32_bf16 v[20:23], v[166:169], v[198:201], v[20:23]
	v_mfma_f32_16x16x32_bf16 v[16:19], v[174:177], v[198:201], v[16:19]
	v_mfma_f32_16x16x32_bf16 v[4:7], v[166:169], v[206:209], v[4:7]
	v_mfma_f32_16x16x32_bf16 v[0:3], v[174:177], v[206:209], v[0:3]
	s_setprio 0
	s_barrier
	s_add_i32 s70, 0, 0x18000
	s_add_i32 s71, 0, 0x1c000
	v_add_u32_e32 v158, s70, v144
	v_add_u32_e32 v174, s71, v144
	ds_read_b128 v[146:149], v158
	ds_read_b128 v[150:153], v158 offset:1024
	ds_read_b128 v[154:157], v158 offset:2048
	ds_read_b128 v[158:161], v158 offset:3072
	ds_read_b128 v[162:165], v174
	ds_read_b128 v[166:169], v174 offset:1024
	ds_read_b128 v[170:173], v174 offset:2048
	ds_read_b128 v[174:177], v174 offset:3072
	s_add_u32 s36, s36, 0x40000
	s_addc_u32 s37, s37, 0
	s_mov_b32 m0, s54
	v_lshl_add_u64 v[216:217], s[36:37], 0, v[134:135]
	global_load_lds_dwordx4 v[216:217], off
	ds_read_b128 v[178:181], v145 offset:32768
	ds_read_b128 v[182:185], v145 offset:33792
	ds_read_b128 v[186:189], v145 offset:34816
	ds_read_b128 v[190:193], v145 offset:35840
	ds_read_b128 v[194:197], v145 offset:36864
	ds_read_b128 v[198:201], v145 offset:37888
	ds_read_b128 v[202:205], v145 offset:38912
	ds_read_b128 v[206:209], v145 offset:39936
	v_lshl_add_u64 v[216:217], s[36:37], 0, v[132:133]
	s_mov_b32 m0, s55
	s_nop 0
	global_load_lds_dwordx4 v[216:217], off
	s_waitcnt vmcnt(8)
	s_waitcnt lgkmcnt(0)
	s_barrier
	s_setprio 1
	s_waitcnt lgkmcnt(0)
	v_mfma_f32_16x16x32_bf16 v[124:127], v[146:149], v[178:181], v[124:127]
	v_mfma_f32_16x16x32_bf16 v[120:123], v[154:157], v[178:181], v[120:123]
	v_mfma_f32_16x16x32_bf16 v[108:111], v[146:149], v[186:189], v[108:111]
	v_mfma_f32_16x16x32_bf16 v[104:107], v[154:157], v[186:189], v[104:107]
	v_mfma_f32_16x16x32_bf16 v[92:95], v[146:149], v[194:197], v[92:95]
	v_mfma_f32_16x16x32_bf16 v[88:91], v[154:157], v[194:197], v[88:91]
	v_mfma_f32_16x16x32_bf16 v[76:79], v[146:149], v[202:205], v[76:79]
	v_mfma_f32_16x16x32_bf16 v[72:75], v[154:157], v[202:205], v[72:75]
	v_mfma_f32_16x16x32_bf16 v[124:127], v[150:153], v[182:185], v[124:127]
	v_mfma_f32_16x16x32_bf16 v[120:123], v[158:161], v[182:185], v[120:123]
	v_mfma_f32_16x16x32_bf16 v[108:111], v[150:153], v[190:193], v[108:111]
	v_mfma_f32_16x16x32_bf16 v[104:107], v[158:161], v[190:193], v[104:107]
	v_mfma_f32_16x16x32_bf16 v[92:95], v[150:153], v[198:201], v[92:95]
	v_mfma_f32_16x16x32_bf16 v[88:91], v[158:161], v[198:201], v[88:91]
	v_mfma_f32_16x16x32_bf16 v[76:79], v[150:153], v[206:209], v[76:79]
	v_mfma_f32_16x16x32_bf16 v[72:75], v[158:161], v[206:209], v[72:75]
	s_setprio 0
	s_setprio 1
	v_mfma_f32_16x16x32_bf16 v[116:119], v[162:165], v[178:181], v[116:119]
	v_mfma_f32_16x16x32_bf16 v[112:115], v[170:173], v[178:181], v[112:115]
	v_mfma_f32_16x16x32_bf16 v[100:103], v[162:165], v[186:189], v[100:103]
	v_mfma_f32_16x16x32_bf16 v[96:99], v[170:173], v[186:189], v[96:99]
	v_mfma_f32_16x16x32_bf16 v[84:87], v[162:165], v[194:197], v[84:87]
	v_mfma_f32_16x16x32_bf16 v[80:83], v[170:173], v[194:197], v[80:83]
	v_mfma_f32_16x16x32_bf16 v[68:71], v[162:165], v[202:205], v[68:71]
	v_mfma_f32_16x16x32_bf16 v[64:67], v[170:173], v[202:205], v[64:67]
	v_mfma_f32_16x16x32_bf16 v[116:119], v[166:169], v[182:185], v[116:119]
	v_mfma_f32_16x16x32_bf16 v[112:115], v[174:177], v[182:185], v[112:115]
	v_mfma_f32_16x16x32_bf16 v[100:103], v[166:169], v[190:193], v[100:103]
	v_mfma_f32_16x16x32_bf16 v[96:99], v[174:177], v[190:193], v[96:99]
	v_mfma_f32_16x16x32_bf16 v[84:87], v[166:169], v[198:201], v[84:87]
	v_mfma_f32_16x16x32_bf16 v[80:83], v[174:177], v[198:201], v[80:83]
	v_mfma_f32_16x16x32_bf16 v[68:71], v[166:169], v[206:209], v[68:71]
	v_mfma_f32_16x16x32_bf16 v[64:67], v[174:177], v[206:209], v[64:67]
	s_setprio 0
	s_barrier
	s_add_i32 s36, s70, s41
	v_lshl_add_u64 v[140:141], v[140:141], 0, s[6:7]
	s_mov_b32 m0, s36
	s_nop 0
	global_load_lds_dwordx4 v[140:141], off
	ds_read_b128 v[178:181], v145 offset:49152
	ds_read_b128 v[182:185], v145 offset:50176
	ds_read_b128 v[186:189], v145 offset:51200
	ds_read_b128 v[190:193], v145 offset:52224
	ds_read_b128 v[194:197], v145 offset:53248
	ds_read_b128 v[198:201], v145 offset:54272
	ds_read_b128 v[202:205], v145 offset:55296
	ds_read_b128 v[206:209], v145 offset:56320
	s_add_i32 m0, s36, 0x2000
	s_add_u32 s34, s34, 0x40080
	v_lshl_add_u64 v[140:141], v[210:211], 0, s[6:7]
	s_addc_u32 s35, s35, 0
	s_add_i32 s36, s71, s41
	global_load_lds_dwordx4 v[140:141], off
	v_lshl_add_u64 v[140:141], s[34:35], 0, v[128:129]
	s_mov_b32 m0, s36
	s_nop 0
	global_load_lds_dwordx4 v[140:141], off
	v_lshl_add_u64 v[140:141], s[34:35], 0, v[130:131]
	s_add_i32 m0, s36, 0x2000
	s_nop 0
	global_load_lds_dwordx4 v[140:141], off
	v_lshl_add_u64 v[140:141], v[212:213], 0, s[6:7]
	s_mov_b32 m0, s57
	s_nop 0
	global_load_lds_dwordx4 v[140:141], off
	v_lshl_add_u64 v[140:141], v[214:215], 0, s[6:7]
	s_mov_b32 m0, s58
	s_nop 0
	global_load_lds_dwordx4 v[140:141], off
	s_waitcnt vmcnt(8)
	s_waitcnt lgkmcnt(0)
	s_barrier
	s_setprio 1
	s_waitcnt lgkmcnt(0)
	v_mfma_f32_16x16x32_bf16 v[60:63], v[146:149], v[178:181], v[60:63]
	v_mfma_f32_16x16x32_bf16 v[56:59], v[154:157], v[178:181], v[56:59]
	v_mfma_f32_16x16x32_bf16 v[44:47], v[146:149], v[186:189], v[44:47]
	v_mfma_f32_16x16x32_bf16 v[40:43], v[154:157], v[186:189], v[40:43]
	v_mfma_f32_16x16x32_bf16 v[28:31], v[146:149], v[194:197], v[28:31]
	v_mfma_f32_16x16x32_bf16 v[24:27], v[154:157], v[194:197], v[24:27]
	v_mfma_f32_16x16x32_bf16 v[12:15], v[146:149], v[202:205], v[12:15]
	v_mfma_f32_16x16x32_bf16 v[8:11], v[154:157], v[202:205], v[8:11]
	v_mfma_f32_16x16x32_bf16 v[60:63], v[150:153], v[182:185], v[60:63]
	v_mfma_f32_16x16x32_bf16 v[56:59], v[158:161], v[182:185], v[56:59]
	v_mfma_f32_16x16x32_bf16 v[44:47], v[150:153], v[190:193], v[44:47]
	v_mfma_f32_16x16x32_bf16 v[40:43], v[158:161], v[190:193], v[40:43]
	v_mfma_f32_16x16x32_bf16 v[28:31], v[150:153], v[198:201], v[28:31]
	v_mfma_f32_16x16x32_bf16 v[24:27], v[158:161], v[198:201], v[24:27]
	v_mfma_f32_16x16x32_bf16 v[12:15], v[150:153], v[206:209], v[12:15]
	v_mfma_f32_16x16x32_bf16 v[8:11], v[158:161], v[206:209], v[8:11]
	s_setprio 0
	s_setprio 1
	v_mfma_f32_16x16x32_bf16 v[52:55], v[162:165], v[178:181], v[52:55]
	v_mfma_f32_16x16x32_bf16 v[48:51], v[170:173], v[178:181], v[48:51]
	v_mfma_f32_16x16x32_bf16 v[36:39], v[162:165], v[186:189], v[36:39]
	v_mfma_f32_16x16x32_bf16 v[32:35], v[170:173], v[186:189], v[32:35]
	v_mfma_f32_16x16x32_bf16 v[20:23], v[162:165], v[194:197], v[20:23]
	v_mfma_f32_16x16x32_bf16 v[16:19], v[170:173], v[194:197], v[16:19]
	v_mfma_f32_16x16x32_bf16 v[4:7], v[162:165], v[202:205], v[4:7]
	v_mfma_f32_16x16x32_bf16 v[0:3], v[170:173], v[202:205], v[0:3]
	v_mfma_f32_16x16x32_bf16 v[52:55], v[166:169], v[182:185], v[52:55]
	v_mfma_f32_16x16x32_bf16 v[48:51], v[174:177], v[182:185], v[48:51]
	v_mfma_f32_16x16x32_bf16 v[36:39], v[166:169], v[190:193], v[36:39]
	v_mfma_f32_16x16x32_bf16 v[32:35], v[174:177], v[190:193], v[32:35]
	v_mfma_f32_16x16x32_bf16 v[20:23], v[166:169], v[198:201], v[20:23]
	v_mfma_f32_16x16x32_bf16 v[16:19], v[174:177], v[198:201], v[16:19]
	v_mfma_f32_16x16x32_bf16 v[4:7], v[166:169], v[206:209], v[4:7]
	v_mfma_f32_16x16x32_bf16 v[0:3], v[174:177], v[206:209], v[0:3]
	s_setprio 0
	s_barrier
	s_add_i32 s66, s66, 2
	s_add_u32 s30, s30, 0x100
	s_addc_u32 s31, s31, 0
	s_add_u32 s64, s64, 0x100
	s_addc_u32 s65, s65, 0
	s_cmp_gt_u32 s66, 13
	s_cbranch_scc0 .LBB0_1766
	s_and_b64 vcc, exec, s[18:19]
	s_cbranch_vccz .LBB0_1769
	s_barrier

.LBB0_1859:
	s_add_i32 s73, s36, 2
	s_add_u32 s34, s30, 0x100
	s_addc_u32 s35, s31, 0
	s_add_i32 s74, 0, 0x10000
	s_cmp_eq_u32 s0, s36
	s_cselect_b32 s41, s25, s35
	s_cselect_b32 s40, s68, s34
	s_cselect_b32 s37, s23, s72
	s_cselect_b32 s36, s70, s71
	s_add_i32 s75, 0, 0x14000
	v_add_u32_e32 v152, s74, v138
	v_add_u32_e32 v168, s75, v138
	ds_read_b128 v[140:143], v152
	ds_read_b128 v[144:147], v152 offset:1024
	ds_read_b128 v[148:151], v152 offset:2048
	ds_read_b128 v[152:155], v152 offset:3072
	ds_read_b128 v[156:159], v168
	ds_read_b128 v[160:163], v168 offset:1024
	ds_read_b128 v[164:167], v168 offset:2048
	ds_read_b128 v[168:171], v168 offset:3072
	v_lshl_add_u64 v[204:205], s[30:31], 0, v[132:133]
	s_add_i32 m0, s56, 0xc000
	s_nop 0
	global_load_lds_dwordx4 v[204:205], off
	ds_read_b128 v[172:175], v139
	ds_read_b128 v[176:179], v139 offset:1024
	ds_read_b128 v[180:183], v139 offset:2048
	ds_read_b128 v[184:187], v139 offset:3072
	ds_read_b128 v[188:191], v139 offset:4096
	ds_read_b128 v[192:195], v139 offset:5120
	ds_read_b128 v[196:199], v139 offset:6144
	ds_read_b128 v[200:203], v139 offset:7168
	v_lshl_add_u64 v[204:205], s[30:31], 0, v[134:135]
	s_add_i32 m0, s56, 0xe000
	s_nop 0
	global_load_lds_dwordx4 v[204:205], off
	s_waitcnt vmcnt(8)
	s_waitcnt lgkmcnt(0)
	s_barrier
	s_setprio 1
	s_waitcnt lgkmcnt(0)
	v_mfma_f32_16x16x32_bf16 v[124:127], v[140:143], v[172:175], v[124:127]
	v_mfma_f32_16x16x32_bf16 v[108:111], v[148:151], v[172:175], v[108:111]
	v_mfma_f32_16x16x32_bf16 v[120:123], v[140:143], v[180:183], v[120:123]
	v_mfma_f32_16x16x32_bf16 v[104:107], v[148:151], v[180:183], v[104:107]
	v_mfma_f32_16x16x32_bf16 v[116:119], v[140:143], v[188:191], v[116:119]
	v_mfma_f32_16x16x32_bf16 v[100:103], v[148:151], v[188:191], v[100:103]
	v_mfma_f32_16x16x32_bf16 v[112:115], v[140:143], v[196:199], v[112:115]
	v_mfma_f32_16x16x32_bf16 v[96:99], v[148:151], v[196:199], v[96:99]
	v_mfma_f32_16x16x32_bf16 v[124:127], v[144:147], v[176:179], v[124:127]
	v_mfma_f32_16x16x32_bf16 v[108:111], v[152:155], v[176:179], v[108:111]
	v_mfma_f32_16x16x32_bf16 v[120:123], v[144:147], v[184:187], v[120:123]
	v_mfma_f32_16x16x32_bf16 v[104:107], v[152:155], v[184:187], v[104:107]
	v_mfma_f32_16x16x32_bf16 v[116:119], v[144:147], v[192:195], v[116:119]
	v_mfma_f32_16x16x32_bf16 v[100:103], v[152:155], v[192:195], v[100:103]
	v_mfma_f32_16x16x32_bf16 v[112:115], v[144:147], v[200:203], v[112:115]
	v_mfma_f32_16x16x32_bf16 v[96:99], v[152:155], v[200:203], v[96:99]
	s_setprio 0
	s_setprio 1
	v_mfma_f32_16x16x32_bf16 v[92:95], v[156:159], v[172:175], v[92:95]
	v_mfma_f32_16x16x32_bf16 v[76:79], v[164:167], v[172:175], v[76:79]
	v_mfma_f32_16x16x32_bf16 v[88:91], v[156:159], v[180:183], v[88:91]
	v_mfma_f32_16x16x32_bf16 v[72:75], v[164:167], v[180:183], v[72:75]
	v_mfma_f32_16x16x32_bf16 v[84:87], v[156:159], v[188:191], v[84:87]
	v_mfma_f32_16x16x32_bf16 v[68:71], v[164:167], v[188:191], v[68:71]
	v_mfma_f32_16x16x32_bf16 v[80:83], v[156:159], v[196:199], v[80:83]
	v_mfma_f32_16x16x32_bf16 v[64:67], v[164:167], v[196:199], v[64:67]
	v_mfma_f32_16x16x32_bf16 v[92:95], v[160:163], v[176:179], v[92:95]
	v_mfma_f32_16x16x32_bf16 v[76:79], v[168:171], v[176:179], v[76:79]
	v_mfma_f32_16x16x32_bf16 v[88:91], v[160:163], v[184:187], v[88:91]
	v_mfma_f32_16x16x32_bf16 v[72:75], v[168:171], v[184:187], v[72:75]
	v_mfma_f32_16x16x32_bf16 v[84:87], v[160:163], v[192:195], v[84:87]
	v_mfma_f32_16x16x32_bf16 v[68:71], v[168:171], v[192:195], v[68:71]
	v_mfma_f32_16x16x32_bf16 v[80:83], v[160:163], v[200:203], v[80:83]
	v_mfma_f32_16x16x32_bf16 v[64:67], v[168:171], v[200:203], v[64:67]
	s_setprio 0
	s_barrier
	s_add_i32 s30, s74, s54
	v_lshl_add_u64 v[204:205], s[36:37], 0, v[128:129]
	s_mov_b32 m0, s30
	s_nop 0
	global_load_lds_dwordx4 v[204:205], off
	ds_read_b128 v[172:175], v139 offset:16384
	ds_read_b128 v[176:179], v139 offset:17408
	ds_read_b128 v[180:183], v139 offset:18432
	ds_read_b128 v[184:187], v139 offset:19456
	ds_read_b128 v[188:191], v139 offset:20480
	ds_read_b128 v[192:195], v139 offset:21504
	ds_read_b128 v[196:199], v139 offset:22528
	ds_read_b128 v[200:203], v139 offset:23552
	s_add_i32 m0, s30, 0x2000
	s_add_u32 s30, s36, 0x100000
	v_lshl_add_u64 v[206:207], s[36:37], 0, v[130:131]
	s_addc_u32 s31, s37, 0
	s_add_i32 s74, s75, s54
	global_load_lds_dwordx4 v[206:207], off
	v_lshl_add_u64 v[208:209], s[30:31], 0, v[128:129]
	s_mov_b32 m0, s74
	v_lshl_add_u64 v[210:211], s[40:41], 0, v[130:131]
	global_load_lds_dwordx4 v[208:209], off
	v_lshl_add_u64 v[208:209], s[30:31], 0, v[130:131]
	s_add_i32 m0, s74, 0x2000
	s_nop 0
	global_load_lds_dwordx4 v[208:209], off
	v_lshl_add_u64 v[208:209], s[40:41], 0, v[128:129]
	s_mov_b32 m0, s56
	s_nop 0
	global_load_lds_dwordx4 v[208:209], off
	s_mov_b32 m0, s58
	s_nop 0
	global_load_lds_dwordx4 v[210:211], off
	s_waitcnt vmcnt(8)
	s_waitcnt lgkmcnt(0)
	s_barrier
	s_setprio 1
	s_waitcnt lgkmcnt(0)
	v_mfma_f32_16x16x32_bf16 v[60:63], v[140:143], v[172:175], v[60:63]
	v_mfma_f32_16x16x32_bf16 v[44:47], v[148:151], v[172:175], v[44:47]
	v_mfma_f32_16x16x32_bf16 v[56:59], v[140:143], v[180:183], v[56:59]
	v_mfma_f32_16x16x32_bf16 v[40:43], v[148:151], v[180:183], v[40:43]
	v_mfma_f32_16x16x32_bf16 v[52:55], v[140:143], v[188:191], v[52:55]
	v_mfma_f32_16x16x32_bf16 v[36:39], v[148:151], v[188:191], v[36:39]
	v_mfma_f32_16x16x32_bf16 v[48:51], v[140:143], v[196:199], v[48:51]
	v_mfma_f32_16x16x32_bf16 v[32:35], v[148:151], v[196:199], v[32:35]
	v_mfma_f32_16x16x32_bf16 v[60:63], v[144:147], v[176:179], v[60:63]
	v_mfma_f32_16x16x32_bf16 v[44:47], v[152:155], v[176:179], v[44:47]
	v_mfma_f32_16x16x32_bf16 v[56:59], v[144:147], v[184:187], v[56:59]
	v_mfma_f32_16x16x32_bf16 v[40:43], v[152:155], v[184:187], v[40:43]
	v_mfma_f32_16x16x32_bf16 v[52:55], v[144:147], v[192:195], v[52:55]
	v_mfma_f32_16x16x32_bf16 v[36:39], v[152:155], v[192:195], v[36:39]
	v_mfma_f32_16x16x32_bf16 v[48:51], v[144:147], v[200:203], v[48:51]
	v_mfma_f32_16x16x32_bf16 v[32:35], v[152:155], v[200:203], v[32:35]
	s_setprio 0
	s_setprio 1
	v_mfma_f32_16x16x32_bf16 v[28:31], v[156:159], v[172:175], v[28:31]
	v_mfma_f32_16x16x32_bf16 v[12:15], v[164:167], v[172:175], v[12:15]
	v_mfma_f32_16x16x32_bf16 v[24:27], v[156:159], v[180:183], v[24:27]
	v_mfma_f32_16x16x32_bf16 v[8:11], v[164:167], v[180:183], v[8:11]
	v_mfma_f32_16x16x32_bf16 v[20:23], v[156:159], v[188:191], v[20:23]
	v_mfma_f32_16x16x32_bf16 v[4:7], v[164:167], v[188:191], v[4:7]
	v_mfma_f32_16x16x32_bf16 v[16:19], v[156:159], v[196:199], v[16:19]
	v_mfma_f32_16x16x32_bf16 v[0:3], v[164:167], v[196:199], v[0:3]
	v_mfma_f32_16x16x32_bf16 v[28:31], v[160:163], v[176:179], v[28:31]
	v_mfma_f32_16x16x32_bf16 v[12:15], v[168:171], v[176:179], v[12:15]
	v_mfma_f32_16x16x32_bf16 v[24:27], v[160:163], v[184:187], v[24:27]
	v_mfma_f32_16x16x32_bf16 v[8:11], v[168:171], v[184:187], v[8:11]
	v_mfma_f32_16x16x32_bf16 v[20:23], v[160:163], v[192:195], v[20:23]
	v_mfma_f32_16x16x32_bf16 v[4:7], v[168:171], v[192:195], v[4:7]
	v_mfma_f32_16x16x32_bf16 v[16:19], v[160:163], v[200:203], v[16:19]
	v_mfma_f32_16x16x32_bf16 v[0:3], v[168:171], v[200:203], v[0:3]
	s_setprio 0
	s_barrier
	s_add_i32 s74, 0, 0x18000
	s_add_i32 s75, 0, 0x1c000
	v_add_u32_e32 v152, s74, v138
	v_add_u32_e32 v168, s75, v138
	ds_read_b128 v[140:143], v152
	ds_read_b128 v[144:147], v152 offset:1024
	ds_read_b128 v[148:151], v152 offset:2048
	ds_read_b128 v[152:155], v152 offset:3072
	ds_read_b128 v[156:159], v168
	ds_read_b128 v[160:163], v168 offset:1024
	ds_read_b128 v[164:167], v168 offset:2048
	ds_read_b128 v[168:171], v168 offset:3072
	s_add_u32 s30, s40, 0x100000
	s_addc_u32 s31, s41, 0
	s_mov_b32 m0, s59
	v_lshl_add_u64 v[212:213], s[30:31], 0, v[128:129]
	global_load_lds_dwordx4 v[212:213], off
	ds_read_b128 v[172:175], v139 offset:32768
	ds_read_b128 v[176:179], v139 offset:33792
	ds_read_b128 v[180:183], v139 offset:34816
	ds_read_b128 v[184:187], v139 offset:35840
	ds_read_b128 v[188:191], v139 offset:36864
	ds_read_b128 v[192:195], v139 offset:37888
	ds_read_b128 v[196:199], v139 offset:38912
	ds_read_b128 v[200:203], v139 offset:39936
	v_lshl_add_u64 v[212:213], s[30:31], 0, v[130:131]
	s_mov_b32 m0, s60
	s_nop 0
	global_load_lds_dwordx4 v[212:213], off
	s_waitcnt vmcnt(8)
	s_waitcnt lgkmcnt(0)
	s_barrier
	s_setprio 1
	s_waitcnt lgkmcnt(0)
	v_mfma_f32_16x16x32_bf16 v[124:127], v[140:143], v[172:175], v[124:127]
	v_mfma_f32_16x16x32_bf16 v[108:111], v[148:151], v[172:175], v[108:111]
	v_mfma_f32_16x16x32_bf16 v[120:123], v[140:143], v[180:183], v[120:123]
	v_mfma_f32_16x16x32_bf16 v[104:107], v[148:151], v[180:183], v[104:107]
	v_mfma_f32_16x16x32_bf16 v[116:119], v[140:143], v[188:191], v[116:119]
	v_mfma_f32_16x16x32_bf16 v[100:103], v[148:151], v[188:191], v[100:103]
	v_mfma_f32_16x16x32_bf16 v[112:115], v[140:143], v[196:199], v[112:115]
	v_mfma_f32_16x16x32_bf16 v[96:99], v[148:151], v[196:199], v[96:99]
	v_mfma_f32_16x16x32_bf16 v[124:127], v[144:147], v[176:179], v[124:127]
	v_mfma_f32_16x16x32_bf16 v[108:111], v[152:155], v[176:179], v[108:111]
	v_mfma_f32_16x16x32_bf16 v[120:123], v[144:147], v[184:187], v[120:123]
	v_mfma_f32_16x16x32_bf16 v[104:107], v[152:155], v[184:187], v[104:107]
	v_mfma_f32_16x16x32_bf16 v[116:119], v[144:147], v[192:195], v[116:119]
	v_mfma_f32_16x16x32_bf16 v[100:103], v[152:155], v[192:195], v[100:103]
	v_mfma_f32_16x16x32_bf16 v[112:115], v[144:147], v[200:203], v[112:115]
	v_mfma_f32_16x16x32_bf16 v[96:99], v[152:155], v[200:203], v[96:99]
	s_setprio 0
	s_setprio 1
	v_mfma_f32_16x16x32_bf16 v[92:95], v[156:159], v[172:175], v[92:95]
	v_mfma_f32_16x16x32_bf16 v[76:79], v[164:167], v[172:175], v[76:79]
	v_mfma_f32_16x16x32_bf16 v[88:91], v[156:159], v[180:183], v[88:91]
	v_mfma_f32_16x16x32_bf16 v[72:75], v[164:167], v[180:183], v[72:75]
	v_mfma_f32_16x16x32_bf16 v[84:87], v[156:159], v[188:191], v[84:87]
	v_mfma_f32_16x16x32_bf16 v[68:71], v[164:167], v[188:191], v[68:71]
	v_mfma_f32_16x16x32_bf16 v[80:83], v[156:159], v[196:199], v[80:83]
	v_mfma_f32_16x16x32_bf16 v[64:67], v[164:167], v[196:199], v[64:67]
	v_mfma_f32_16x16x32_bf16 v[92:95], v[160:163], v[176:179], v[92:95]
	v_mfma_f32_16x16x32_bf16 v[76:79], v[168:171], v[176:179], v[76:79]
	v_mfma_f32_16x16x32_bf16 v[88:91], v[160:163], v[184:187], v[88:91]
	v_mfma_f32_16x16x32_bf16 v[72:75], v[168:171], v[184:187], v[72:75]
	v_mfma_f32_16x16x32_bf16 v[84:87], v[160:163], v[192:195], v[84:87]
	v_mfma_f32_16x16x32_bf16 v[68:71], v[168:171], v[192:195], v[68:71]
	v_mfma_f32_16x16x32_bf16 v[80:83], v[160:163], v[200:203], v[80:83]
	v_mfma_f32_16x16x32_bf16 v[64:67], v[168:171], v[200:203], v[64:67]
	s_setprio 0
	s_barrier
	s_add_i32 s30, s74, s54
	v_lshl_add_u64 v[204:205], v[204:205], 0, s[6:7]
	s_mov_b32 m0, s30
	s_nop 0
	global_load_lds_dwordx4 v[204:205], off
	ds_read_b128 v[172:175], v139 offset:49152
	ds_read_b128 v[176:179], v139 offset:50176
	ds_read_b128 v[180:183], v139 offset:51200
	ds_read_b128 v[184:187], v139 offset:52224
	ds_read_b128 v[188:191], v139 offset:53248
	ds_read_b128 v[192:195], v139 offset:54272
	ds_read_b128 v[196:199], v139 offset:55296
	ds_read_b128 v[200:203], v139 offset:56320
	s_add_i32 m0, s30, 0x2000
	s_add_u32 s30, s36, 0x100080
	v_lshl_add_u64 v[204:205], v[206:207], 0, s[6:7]
	s_addc_u32 s31, s37, 0
	s_add_i32 s36, s75, s54
	global_load_lds_dwordx4 v[204:205], off
	v_lshl_add_u64 v[204:205], s[30:31], 0, v[128:129]
	s_mov_b32 m0, s36
	s_nop 0
	global_load_lds_dwordx4 v[204:205], off
	v_lshl_add_u64 v[204:205], s[30:31], 0, v[130:131]
	s_add_i32 m0, s36, 0x2000
	s_nop 0
	global_load_lds_dwordx4 v[204:205], off
	v_lshl_add_u64 v[204:205], v[208:209], 0, s[6:7]
	s_mov_b32 m0, s61
	s_nop 0
	global_load_lds_dwordx4 v[204:205], off
	v_lshl_add_u64 v[204:205], v[210:211], 0, s[6:7]
	s_mov_b32 m0, s62
	s_nop 0
	global_load_lds_dwordx4 v[204:205], off
	s_waitcnt vmcnt(8)
	s_waitcnt lgkmcnt(0)
	s_barrier
	s_setprio 1
	s_waitcnt lgkmcnt(0)
	v_mfma_f32_16x16x32_bf16 v[60:63], v[140:143], v[172:175], v[60:63]
	v_mfma_f32_16x16x32_bf16 v[44:47], v[148:151], v[172:175], v[44:47]
	v_mfma_f32_16x16x32_bf16 v[56:59], v[140:143], v[180:183], v[56:59]
	v_mfma_f32_16x16x32_bf16 v[40:43], v[148:151], v[180:183], v[40:43]
	v_mfma_f32_16x16x32_bf16 v[52:55], v[140:143], v[188:191], v[52:55]
	v_mfma_f32_16x16x32_bf16 v[36:39], v[148:151], v[188:191], v[36:39]
	v_mfma_f32_16x16x32_bf16 v[48:51], v[140:143], v[196:199], v[48:51]
	v_mfma_f32_16x16x32_bf16 v[32:35], v[148:151], v[196:199], v[32:35]
	v_mfma_f32_16x16x32_bf16 v[60:63], v[144:147], v[176:179], v[60:63]
	v_mfma_f32_16x16x32_bf16 v[44:47], v[152:155], v[176:179], v[44:47]
	v_mfma_f32_16x16x32_bf16 v[56:59], v[144:147], v[184:187], v[56:59]
	v_mfma_f32_16x16x32_bf16 v[40:43], v[152:155], v[184:187], v[40:43]
	v_mfma_f32_16x16x32_bf16 v[52:55], v[144:147], v[192:195], v[52:55]
	v_mfma_f32_16x16x32_bf16 v[36:39], v[152:155], v[192:195], v[36:39]
	v_mfma_f32_16x16x32_bf16 v[48:51], v[144:147], v[200:203], v[48:51]
	v_mfma_f32_16x16x32_bf16 v[32:35], v[152:155], v[200:203], v[32:35]
	s_setprio 0
	s_setprio 1
	v_mfma_f32_16x16x32_bf16 v[28:31], v[156:159], v[172:175], v[28:31]
	v_mfma_f32_16x16x32_bf16 v[12:15], v[164:167], v[172:175], v[12:15]
	v_mfma_f32_16x16x32_bf16 v[24:27], v[156:159], v[180:183], v[24:27]
	v_mfma_f32_16x16x32_bf16 v[8:11], v[164:167], v[180:183], v[8:11]
	v_mfma_f32_16x16x32_bf16 v[20:23], v[156:159], v[188:191], v[20:23]
	v_mfma_f32_16x16x32_bf16 v[4:7], v[164:167], v[188:191], v[4:7]
	v_mfma_f32_16x16x32_bf16 v[16:19], v[156:159], v[196:199], v[16:19]
	v_mfma_f32_16x16x32_bf16 v[0:3], v[164:167], v[196:199], v[0:3]
	v_mfma_f32_16x16x32_bf16 v[28:31], v[160:163], v[176:179], v[28:31]
	v_mfma_f32_16x16x32_bf16 v[12:15], v[168:171], v[176:179], v[12:15]
	v_mfma_f32_16x16x32_bf16 v[24:27], v[160:163], v[184:187], v[24:27]
	v_mfma_f32_16x16x32_bf16 v[8:11], v[168:171], v[184:187], v[8:11]
	v_mfma_f32_16x16x32_bf16 v[20:23], v[160:163], v[192:195], v[20:23]
	v_mfma_f32_16x16x32_bf16 v[4:7], v[168:171], v[192:195], v[4:7]
	v_mfma_f32_16x16x32_bf16 v[16:19], v[160:163], v[200:203], v[16:19]
	v_mfma_f32_16x16x32_bf16 v[0:3], v[168:171], v[200:203], v[0:3]
	s_setprio 0
	s_barrier
	s_add_u32 s71, s71, 0x100
	s_addc_u32 s72, s72, 0
	s_cmp_ge_u32 s73, s67
	s_mov_b64 s[30:31], s[34:35]
	s_mov_b32 s36, s73
	s_cbranch_scc0 .LBB0_1859
	s_andn2_b64 vcc, exec, s[48:49]
	s_cbranch_vccnz .LBB0_1851
	v_mov_b32_e32 v0, 0
	s_mov_b32 s64, s22
	s_mov_b32 s63, s24
	s_mov_b64 s[18:19], s[28:29]
	s_mov_b64 s[20:21], s[26:27]
	s_mov_b32 s65, s66
	v_mov_b32_e32 v1, v0
	v_mov_b32_e32 v2, v0
	v_mov_b32_e32 v3, v0
	v_mov_b32_e32 v16, v0
	v_mov_b32_e32 v17, v0
	v_mov_b32_e32 v18, v0
	v_mov_b32_e32 v19, v0
	v_mov_b32_e32 v4, v0
	v_mov_b32_e32 v5, v0
	v_mov_b32_e32 v6, v0
	v_mov_b32_e32 v7, v0
	v_mov_b32_e32 v20, v0
	v_mov_b32_e32 v21, v0
	v_mov_b32_e32 v22, v0
	v_mov_b32_e32 v23, v0
	v_mov_b32_e32 v8, v0
	v_mov_b32_e32 v9, v0
	v_mov_b32_e32 v10, v0
	v_mov_b32_e32 v11, v0
	v_mov_b32_e32 v24, v0
	v_mov_b32_e32 v25, v0
	v_mov_b32_e32 v26, v0
	v_mov_b32_e32 v27, v0
	v_mov_b32_e32 v12, v0
	v_mov_b32_e32 v13, v0
	v_mov_b32_e32 v14, v0
	v_mov_b32_e32 v15, v0
	v_mov_b32_e32 v28, v0
	v_mov_b32_e32 v29, v0
	v_mov_b32_e32 v30, v0
	v_mov_b32_e32 v31, v0
	v_mov_b32_e32 v32, v0
	v_mov_b32_e32 v33, v0
	v_mov_b32_e32 v34, v0
	v_mov_b32_e32 v35, v0
	v_mov_b32_e32 v48, v0
	v_mov_b32_e32 v49, v0
	v_mov_b32_e32 v50, v0
	v_mov_b32_e32 v51, v0
	v_mov_b32_e32 v36, v0
	v_mov_b32_e32 v37, v0
	v_mov_b32_e32 v38, v0
	v_mov_b32_e32 v39, v0
	v_mov_b32_e32 v52, v0
	v_mov_b32_e32 v53, v0
	v_mov_b32_e32 v54, v0
	v_mov_b32_e32 v55, v0
	v_mov_b32_e32 v40, v0
	v_mov_b32_e32 v41, v0
	v_mov_b32_e32 v42, v0
	v_mov_b32_e32 v43, v0
	v_mov_b32_e32 v56, v0
	v_mov_b32_e32 v57, v0
	v_mov_b32_e32 v58, v0
	v_mov_b32_e32 v59, v0
	v_mov_b32_e32 v44, v0
	v_mov_b32_e32 v45, v0
	v_mov_b32_e32 v46, v0
	v_mov_b32_e32 v47, v0
	v_mov_b32_e32 v60, v0
	v_mov_b32_e32 v61, v0
	v_mov_b32_e32 v62, v0
	v_mov_b32_e32 v63, v0
	v_mov_b32_e32 v64, v0
	v_mov_b32_e32 v65, v0
	v_mov_b32_e32 v66, v0
	v_mov_b32_e32 v67, v0
	v_mov_b32_e32 v80, v0
	v_mov_b32_e32 v81, v0
	v_mov_b32_e32 v82, v0
	v_mov_b32_e32 v83, v0
	v_mov_b32_e32 v68, v0
	v_mov_b32_e32 v69, v0
	v_mov_b32_e32 v70, v0
	v_mov_b32_e32 v71, v0
	v_mov_b32_e32 v84, v0
	v_mov_b32_e32 v85, v0
	v_mov_b32_e32 v86, v0
	v_mov_b32_e32 v87, v0
	v_mov_b32_e32 v72, v0
	v_mov_b32_e32 v73, v0
	v_mov_b32_e32 v74, v0
	v_mov_b32_e32 v75, v0
	v_mov_b32_e32 v88, v0
	v_mov_b32_e32 v89, v0
	v_mov_b32_e32 v90, v0
	v_mov_b32_e32 v91, v0
	v_mov_b32_e32 v76, v0
	v_mov_b32_e32 v77, v0
	v_mov_b32_e32 v78, v0
	v_mov_b32_e32 v79, v0
	v_mov_b32_e32 v92, v0
	v_mov_b32_e32 v93, v0
	v_mov_b32_e32 v94, v0
	v_mov_b32_e32 v95, v0
	v_mov_b32_e32 v96, v0
	v_mov_b32_e32 v97, v0
	v_mov_b32_e32 v98, v0
	v_mov_b32_e32 v99, v0
	v_mov_b32_e32 v112, v0
	v_mov_b32_e32 v113, v0
	v_mov_b32_e32 v114, v0
	v_mov_b32_e32 v115, v0
	v_mov_b32_e32 v100, v0
	v_mov_b32_e32 v101, v0
	v_mov_b32_e32 v102, v0
	v_mov_b32_e32 v103, v0
	v_mov_b32_e32 v116, v0
	v_mov_b32_e32 v117, v0
	v_mov_b32_e32 v118, v0
	v_mov_b32_e32 v119, v0
	v_mov_b32_e32 v104, v0
	v_mov_b32_e32 v105, v0
	v_mov_b32_e32 v106, v0
	v_mov_b32_e32 v107, v0
	v_mov_b32_e32 v120, v0
	v_mov_b32_e32 v121, v0
	v_mov_b32_e32 v122, v0
	v_mov_b32_e32 v123, v0
	v_mov_b32_e32 v108, v0
	v_mov_b32_e32 v109, v0
	v_mov_b32_e32 v110, v0
	v_mov_b32_e32 v111, v0
	v_mov_b32_e32 v124, v0
	v_mov_b32_e32 v125, v0
	v_mov_b32_e32 v126, v0
	v_mov_b32_e32 v127, v0
	s_branch .LBB0_1851
